# attention K/V loop: ring slot made a compile-time constant by emitting the body twice (selected by one scalar bit test per iteration); all 19 per-iteration LDS address adds become immediate ds offsets
# speedup vs baseline: 1.0067x; 1.0040x over previous
; #define PUBLISH(n) do { asm volatile("s_waitcnt vmcnt(" #n ")" ::: "memory"); asm volatile("s_waitcnt lgkmcnt(0)" ::: "memory"); __builtin_amdgcn_s_barrier(); SBAR(); } while (0)
; __device__ __forceinline__ void load_q_normed(const bf16* Qw, const float* qnw, const float2* rope, int trow, int hi, bf16x8* qr) {
;     ...
;   for (int d0 = 0; d0 < 8; ++d0) { u32x4 w = {cvtpk(v[d0][0], v[d0][1]), cvtpk(v[d0][2], v[d0][3]), cvtpk(v[d0][4], v[d0][5]), cvtpk(v[d0][6], v[d0][7])}; qr[d0] = *reinterpret_cast<bf16x8*>(&w); }
; template <typename TQ> ...
;     ...
;   for (int i = 0; i < 2; ++i) { const int P = wid * 1024 + lane * 16 + i * 8192;
;     { const int row = P >> 8, colB = (P & 255) ^ ((row & 7) << 4); koff[i] = row * LDK + (colB >> 1); }
;     { const int sub = P >> 9, k = (sub >> 2) * 8 + ((lane & 31) >> 2), c = (sub & 3) * 32 + (lane & 3) * 8; voff[i] = k * LDK + c; } }
;     ...
;   f32x16 pA0, pA1, pB0, pB1; float mnA, mnB, alA, alB; bf16x8 pa0, pa1, pa2, pa3; const int NT = seq / KVBLK;
;   DMA_TILE(0, 0); DMA_TILE(1, 1);
;   PUBLISH(4);
.LBB0_459:
	s_or_b64 exec, exec, s[40:41]
	s_lshl_b64 s[38:39], s[38:39], 12
	s_add_u32 s40, s48, s38
	s_addc_u32 s41, s49, s39
	s_lshl_b32 s42, s42, 8
	s_add_u32 s40, s40, s42
	s_addc_u32 s41, s41, 0
	s_lshl_b32 s33, s33, 10
	v_cvt_pk_bf16_f32 v136, v64, v65
	v_cvt_pk_bf16_f32 v137, v62, v63
	v_cvt_pk_bf16_f32 v138, v60, v61
	v_cvt_pk_bf16_f32 v139, v58, v59
	v_cvt_pk_bf16_f32 v140, v56, v57
	v_cvt_pk_bf16_f32 v141, v54, v55
	v_cvt_pk_bf16_f32 v142, v52, v53
	v_cvt_pk_bf16_f32 v143, v50, v51
	v_cvt_pk_bf16_f32 v132, v48, v49
	v_cvt_pk_bf16_f32 v133, v46, v47
	v_cvt_pk_bf16_f32 v134, v44, v45
	v_cvt_pk_bf16_f32 v135, v42, v43
	v_cvt_pk_bf16_f32 v128, v40, v41
	v_cvt_pk_bf16_f32 v129, v38, v39
	v_cvt_pk_bf16_f32 v130, v36, v37
	v_cvt_pk_bf16_f32 v131, v34, v35
	v_cvt_pk_bf16_f32 v124, v32, v33
	v_cvt_pk_bf16_f32 v125, v30, v31
	v_cvt_pk_bf16_f32 v126, v28, v29
	v_cvt_pk_bf16_f32 v127, v26, v27
	v_cvt_pk_bf16_f32 v120, v24, v25
	v_cvt_pk_bf16_f32 v121, v22, v23
	v_cvt_pk_bf16_f32 v122, v20, v21
	v_cvt_pk_bf16_f32 v123, v18, v19
	v_cvt_pk_bf16_f32 v116, v16, v17
	v_cvt_pk_bf16_f32 v117, v14, v15
	v_cvt_pk_bf16_f32 v118, v12, v13
	v_cvt_pk_bf16_f32 v119, v10, v11
	v_cvt_pk_bf16_f32 v112, v8, v9
	v_cvt_pk_bf16_f32 v113, v6, v7
	v_cvt_pk_bf16_f32 v114, v4, v5
	v_cvt_pk_bf16_f32 v115, v0, v1
	v_or_b32_e32 v1, s33, v172
	v_lshrrev_b32_e32 v0, 4, v1
	v_ashrrev_i32_e32 v2, 8, v1
	v_and_b32_e32 v36, 0x60, v0
	v_lshlrev_b32_e32 v0, 4, v2
	v_add_u32_e32 v1, 0x2000, v1
	v_bitop3_b32 v0, v0, v173, s45 bitop3:0x6c
	v_ashrrev_i32_e32 v1, 8, v1
	v_lshlrev_b32_e32 v37, 11, v2
	v_lshrrev_b32_e32 v0, 1, v0
	v_lshlrev_b32_e32 v4, 4, v1
	v_or_b32_e32 v3, v36, v175
	v_or_b32_e32 v0, v0, v37
	v_bitop3_b32 v4, v4, v173, s45 bitop3:0x6c
	v_lshlrev_b32_e32 v38, 11, v1
	v_and_or_b32 v1, v1, s56, v174
	v_lshrrev_b32_e32 v4, 1, v4
	v_lshl_or_b32 v6, v1, 11, v3
	v_ashrrev_i32_e32 v1, 31, v0
	v_or_b32_e32 v4, v4, v38
	v_lshlrev_b64 v[156:157], 1, v[0:1]
	v_and_or_b32 v2, v2, s56, v174
	v_lshl_add_u64 v[0:1], s[40:41], 0, v[156:157]
	s_add_i32 s67, s57, s33
	v_ashrrev_i32_e32 v5, 31, v4
	v_lshl_or_b32 v2, v2, 11, v3
	v_lshl_add_u64 v[0:1], v[0:1], 0, s[16:17]
	s_mov_b32 m0, s67
	v_lshlrev_b64 v[158:159], 1, v[4:5]
	global_load_lds_dwordx4 v[0:1], off
	v_lshl_add_u64 v[0:1], s[40:41], 0, v[158:159]
	s_add_i32 s72, s33, 0
	v_ashrrev_i32_e32 v3, 31, v2
	v_lshl_add_u64 v[0:1], v[0:1], 0, s[16:17]
	s_add_i32 m0, s72, 0x12000
	v_lshlrev_b64 v[32:33], 1, v[2:3]
	global_load_lds_dwordx4 v[0:1], off
	v_lshl_add_u64 v[0:1], s[40:41], 0, v[32:33]
	v_lshl_add_u64 v[0:1], v[0:1], 0, s[18:19]
	s_mov_b32 m0, s72
	v_ashrrev_i32_e32 v7, 31, v6
	global_load_lds_dwordx4 v[0:1], off
	s_add_i32 m0, s72, 0x2000
	v_lshlrev_b64 v[34:35], 1, v[6:7]
	s_add_u32 s74, s40, 0x40c00
	v_lshl_add_u64 v[0:1], s[40:41], 0, v[34:35]
	s_addc_u32 s75, s41, 0
	v_lshl_add_u64 v[0:1], v[0:1], 0, s[18:19]
	s_add_u32 s76, s40, 0x40e00
	global_load_lds_dwordx4 v[0:1], off
	s_addc_u32 s77, s41, 0
	v_lshl_add_u64 v[0:1], s[74:75], 0, v[156:157]
	s_add_i32 m0, s72, 0x14000
	s_mov_b32 s73, 4
	global_load_lds_dwordx4 v[0:1], off
	v_lshl_add_u64 v[0:1], s[74:75], 0, v[158:159]
	s_add_i32 m0, s72, 0x16000
	s_nop 0
	global_load_lds_dwordx4 v[0:1], off
	v_lshl_add_u64 v[0:1], s[76:77], 0, v[32:33]
	s_add_i32 m0, s72, 0x4000
	s_nop 0
	global_load_lds_dwordx4 v[0:1], off
	v_lshl_add_u64 v[0:1], s[76:77], 0, v[34:35]
	s_add_i32 m0, s72, 0x6000
	s_nop 0
	global_load_lds_dwordx4 v[0:1], off
	s_waitcnt vmcnt(4)
	s_waitcnt lgkmcnt(0)
	s_barrier
; #define PUBLISH(n) do { asm volatile("s_waitcnt vmcnt(" #n ")" ::: "memory"); asm volatile("s_waitcnt lgkmcnt(0)" ::: "memory"); __builtin_amdgcn_s_barrier(); SBAR(); } while (0)
; template <typename TQ> ...
;     ...
;   qkt(pA0, pA1, (const bf16*)K_lds, qr, r32, hi); partialSM<true>(pA0, pA1, m_reg, mnA, alA);
;   DMA_TILE(2, 2);
;   PUBLISH(4);
;   for (int j = 1; j + 1 < NT; j += 2) {
	v_add_u32_e32 v4, s57, v178
	ds_read_b128 v[0:3], v4
	ds_read_b128 v[16:19], v4 offset:8192
	v_add_u32_e32 v20, s57, v179
	v_add_u32_e32 v24, s57, v184
	s_add_u32 s74, s40, 0x80c00
	s_waitcnt lgkmcnt(0)
	v_mfma_f32_32x32x16_bf16 v[0:15], v[0:3], v[136:139], 0
	s_addc_u32 s75, s41, 0
	s_add_u32 s40, s40, 0x80e00
	v_add_u32_e32 v28, s57, v185
	s_addc_u32 s41, s41, 0
	s_add_i32 m0, s72, 0x18000
	s_mov_b32 s33, 0x8000
	v_mfma_f32_32x32x16_bf16 v[64:79], v[16:19], v[136:139], 0
	ds_read_b128 v[16:19], v20
	ds_read_b128 v[20:23], v20 offset:8192
	s_waitcnt lgkmcnt(0)
	v_mfma_f32_32x32x16_bf16 v[0:15], v[16:19], v[140:143], v[0:15]
	v_mfma_f32_32x32x16_bf16 v[64:79], v[20:23], v[140:143], v[64:79]
	v_add_u32_e32 v20, s57, v180
	ds_read_b128 v[16:19], v20
	ds_read_b128 v[20:23], v20 offset:8192
	s_waitcnt lgkmcnt(0)
	v_mfma_f32_32x32x16_bf16 v[0:15], v[16:19], v[132:135], v[0:15]
	v_mfma_f32_32x32x16_bf16 v[64:79], v[20:23], v[132:135], v[64:79]
	v_add_u32_e32 v20, s57, v181
	ds_read_b128 v[16:19], v20
	ds_read_b128 v[20:23], v20 offset:8192
	s_waitcnt lgkmcnt(0)
	v_mfma_f32_32x32x16_bf16 v[0:15], v[16:19], v[128:131], v[0:15]
	v_mfma_f32_32x32x16_bf16 v[64:79], v[20:23], v[128:131], v[64:79]
	v_add_u32_e32 v20, s57, v182
	ds_read_b128 v[16:19], v20
	ds_read_b128 v[20:23], v20 offset:8192
	s_waitcnt lgkmcnt(0)
	v_mfma_f32_32x32x16_bf16 v[0:15], v[16:19], v[124:127], v[0:15]
	v_mfma_f32_32x32x16_bf16 v[64:79], v[20:23], v[124:127], v[64:79]
	v_add_u32_e32 v20, s57, v183
	ds_read_b128 v[16:19], v20
	ds_read_b128 v[20:23], v20 offset:8192
	s_waitcnt lgkmcnt(0)
	v_mfma_f32_32x32x16_bf16 v[0:15], v[16:19], v[120:123], v[0:15]
	v_mfma_f32_32x32x16_bf16 v[64:79], v[20:23], v[120:123], v[64:79]
	ds_read_b128 v[16:19], v24
	ds_read_b128 v[20:23], v24 offset:8192
	ds_read_b128 v[24:27], v28
	ds_read_b128 v[28:31], v28 offset:8192
	s_waitcnt lgkmcnt(0)
	v_mfma_f32_32x32x16_bf16 v[0:15], v[16:19], v[116:119], v[0:15]
	v_lshl_add_u64 v[16:17], s[74:75], 0, v[156:157]
	global_load_lds_dwordx4 v[16:17], off
	v_lshl_add_u64 v[16:17], s[74:75], 0, v[158:159]
	s_add_i32 m0, s72, 0x1a000
	s_nop 0
	global_load_lds_dwordx4 v[16:17], off
	v_lshl_add_u64 v[16:17], s[40:41], 0, v[32:33]
	s_add_i32 m0, s72, 0x8000
	v_mfma_f32_32x32x16_bf16 v[64:79], v[20:23], v[116:119], v[64:79]
	global_load_lds_dwordx4 v[16:17], off
	v_lshl_add_u64 v[16:17], s[40:41], 0, v[34:35]
	s_add_i32 m0, s72, 0xa000
	s_nop 0
	global_load_lds_dwordx4 v[16:17], off
	v_mfma_f32_32x32x16_bf16 v[0:15], v[24:27], v[112:115], v[0:15]
	s_waitcnt vmcnt(4)
	s_waitcnt lgkmcnt(0)
	s_barrier
	v_mfma_f32_32x32x16_bf16 v[64:79], v[28:31], v[112:115], v[64:79]
	s_nop 9
	v_exp_f32_e32 v196, v0
	v_and_or_b32 v0, v38, s59, v188
	v_add_u32_e32 v0, v0, v36
	v_exp_f32_e32 v197, v1
	v_ashrrev_i32_e32 v1, 31, v0
	v_exp_f32_e32 v193, v2
	v_exp_f32_e32 v195, v3
	v_exp_f32_e32 v191, v4
	v_exp_f32_e32 v194, v5
	v_exp_f32_e32 v190, v6
	v_exp_f32_e32 v192, v7
	v_exp_f32_e32 v169, v8
	v_exp_f32_e32 v171, v9
	v_exp_f32_e32 v167, v10
	v_exp_f32_e32 v170, v11
	v_exp_f32_e32 v165, v12
	v_exp_f32_e32 v168, v13
	v_exp_f32_e32 v164, v14
	v_exp_f32_e32 v166, v15
	v_lshlrev_b64 v[160:161], 1, v[0:1]
	v_and_or_b32 v0, v37, s59, v188
	s_or_b32 s38, s38, s42
	v_add_u32_e32 v0, v0, v36
	s_add_u32 s38, s8, s38
	v_ashrrev_i32_e32 v1, 31, v0
	v_mov_b32_e32 v146, 0
	s_addc_u32 s39, s9, s39
	v_lshlrev_b64 v[162:163], 1, v[0:1]
	v_mov_b32_e32 v0, 0
	v_mov_b32_e32 v1, v146
	v_mov_b32_e32 v2, v146
	v_mov_b32_e32 v3, v146
	v_mov_b32_e32 v4, v146
	v_mov_b32_e32 v5, v146
	v_mov_b32_e32 v6, v146
	v_mov_b32_e32 v7, v146
	v_mov_b32_e32 v8, v146
	v_mov_b32_e32 v9, v146
	v_mov_b32_e32 v10, v146
	v_mov_b32_e32 v11, v146
	v_mov_b32_e32 v12, v146
	v_mov_b32_e32 v13, v146
	v_mov_b32_e32 v14, v146
	v_mov_b32_e32 v15, v146
	v_mov_b32_e32 v16, 0
	v_mov_b32_e32 v17, v146
	v_mov_b32_e32 v18, v146
	v_mov_b32_e32 v19, v146
	v_mov_b32_e32 v20, v146
	v_mov_b32_e32 v21, v146
	v_mov_b32_e32 v22, v146
	v_mov_b32_e32 v23, v146
	v_mov_b32_e32 v24, v146
	v_mov_b32_e32 v25, v146
	v_mov_b32_e32 v26, v146
	v_mov_b32_e32 v27, v146
	v_mov_b32_e32 v28, v146
	v_mov_b32_e32 v29, v146
	v_mov_b32_e32 v30, v146
	v_mov_b32_e32 v31, v146
	v_mov_b32_e32 v32, 0
	v_mov_b32_e32 v33, v146
	v_mov_b32_e32 v34, v146
	v_mov_b32_e32 v35, v146
	v_mov_b32_e32 v36, v146
	v_mov_b32_e32 v37, v146
	v_mov_b32_e32 v38, v146
	v_mov_b32_e32 v39, v146
	v_mov_b32_e32 v40, v146
	v_mov_b32_e32 v41, v146
	v_mov_b32_e32 v42, v146
	v_mov_b32_e32 v43, v146
	v_mov_b32_e32 v44, v146
	v_mov_b32_e32 v45, v146
	v_mov_b32_e32 v46, v146
	v_mov_b32_e32 v47, v146
	v_mov_b32_e32 v48, 0
	v_mov_b32_e32 v49, v146
	v_mov_b32_e32 v50, v146
	v_mov_b32_e32 v51, v146
	v_mov_b32_e32 v52, v146
	v_mov_b32_e32 v53, v146
	v_mov_b32_e32 v54, v146
	v_mov_b32_e32 v55, v146
	v_mov_b32_e32 v56, v146
	v_mov_b32_e32 v57, v146
	v_mov_b32_e32 v58, v146
	v_mov_b32_e32 v59, v146
	v_mov_b32_e32 v60, v146
	v_mov_b32_e32 v61, v146
	v_mov_b32_e32 v62, v146
	v_mov_b32_e32 v63, v146
	v_add_u32_e32 v178, 0x10000, v178
	v_add_u32_e32 v179, 0x10000, v179
	v_add_u32_e32 v180, 0x10000, v180
	v_add_u32_e32 v181, 0x10000, v181
	v_add_u32_e32 v182, 0x10000, v182
	v_add_u32_e32 v183, 0x10000, v183
	v_add_u32_e32 v184, 0x10000, v184
	v_add_u32_e32 v185, 0x10000, v185
	s_branch .LBB0_461

; __device__ __forceinline__ void finishSM(f32x16& p0, f32x16& p1, float alpha, float& l_reg, bf16x8& pa0, bf16x8& pa1, bf16x8& pa2, bf16x8& pa3) {
;   for (int r = 0; r < 16; ++r) p1[r] = __builtin_amdgcn_exp2f(p1[r]);
;   float ps = 0; for (int r = 0; r < 16; ++r) ps += p0[r]; for (int r = 0; r < 16; ++r) ps += p1[r];
;   asm volatile("" : "+v"(ps));
;   l_reg = l_reg * alpha + ps;
;     ...
;   PK4(p0, 0, pa0); PK4(p0, 8, pa1); PK4(p1, 0, pa2); PK4(p1, 8, pa3);
;     ...
; }
; __device__ __forceinline__ void qkt(f32x16& p0, f32x16& p1, const bf16* Ks, const bf16x8* qr, int r32, int hi) {
;   p0 = f32x16{}; p1 = f32x16{};
;   for (int d0 = 0; d0 < 8; ++d0) { int cb = (d0 * 16 + hi * 8) * 2;
;     bf16x8 b0 = *reinterpret_cast<const bf16x8*>((const char*)Ks + KSWZ(r32, cb));
;     bf16x8 b1 = *reinterpret_cast<const bf16x8*>((const char*)Ks + KSWZ(32 + r32, cb));
;     p0 = __builtin_amdgcn_mfma_f32_32x32x16_bf16(b0, qr[d0], p0, 0, 0, 0);
;     p1 = __builtin_amdgcn_mfma_f32_32x32x16_bf16(b1, qr[d0], p1, 0, 0, 0); }
; }
; __device__ __forceinline__ int v_st(int k, int c) { const int kk = k;
;   return ((kk >> 3) * 4 + (c >> 5)) * 512 + ((kk & 7) * 32 + (c & 31)) * 2; }
; __device__ __forceinline__ int v_rd_base(int lane) { return ((lane & 3) << 3) | (((lane >> 2) & 3) << 6) | (((lane >> 4) & 1) << 5) | (((lane >> 5) & 1) << 8); }
; template <int OFF> __device__ __forceinline__ s16x4 tr_read(int vb) {
;   s16x4 r; asm volatile("ds_read_b64_tr_b16 %0, %1 offset:%2" : "=&v"(r) : "v"(vb), "i"(OFF) : "memory"); return r;
; }
; template <int D0> __device__ __forceinline__ void pv_one(f32x16& od, int vb, bf16x8 pa0, bf16x8 pa1, bf16x8 pa2, bf16x8 pa3) {
;   const s16x4 l0 = tr_read<v_rd_off(D0, 0, 0)>(vb), h0 = tr_read<v_rd_off(D0, 0, 1)>(vb), l1 = tr_read<v_rd_off(D0, 1, 0)>(vb), h1 = tr_read<v_rd_off(D0, 1, 1)>(vb);
;   const s16x4 l2 = tr_read<v_rd_off(D0, 2, 0)>(vb), h2 = tr_read<v_rd_off(D0, 2, 1)>(vb), l3 = tr_read<v_rd_off(D0, 3, 0)>(vb), h3 = tr_read<v_rd_off(D0, 3, 1)>(vb);
;   asm volatile("s_waitcnt lgkmcnt(0)" ::: "memory"); SBAR();
; template <typename TQ> ...
;     ...
;     SBAR(); qkt(pB0, pB1, (const bf16*)(K_lds + (j & 3) * (int)SHM_K), qr, r32, hi);
;     finishSM(pA0, pA1, alA, l_reg, pa0, pa1, pa2, pa3); SBAR();
;     DMA_TILE(j + 2, (j + 2) & 3); SBAR();
;     pv_d0(o, vb0 + ((j - 1) & 3) * (int)SHM_V, pa0, pa1, pa2, pa3); partialSM<true>(pB0, pB1, m_reg, mnB, alB);
.LBB0_461:
	s_bitcmp1_b32 s73, 1
	s_cbranch_scc1 .Lat461_b_in
	s_mov_b32 s40, s33
	s_addk_i32 s33, 0xc000
	s_and_b32 s42, s33, 0xc000
	s_add_i32 s33, s57, s42
	ds_read_b128 v[80:83], v178 offset:16384
	ds_read_b128 v[84:87], v178 offset:24576
	ds_read_b128 v[198:201], v179 offset:16384
	ds_read_b128 v[202:205], v179 offset:24576
	s_waitcnt lgkmcnt(3)
	v_mfma_f32_32x32x16_bf16 v[96:111], v[80:83], v[136:139], 0
	v_exp_f32_e32 v238, v64
	v_add_f32_e32 v64, 0, v196
	v_add_f32_e32 v64, v197, v64
	v_add_f32_e32 v64, v193, v64
	v_add_f32_e32 v64, v195, v64
	s_waitcnt lgkmcnt(2)
	v_mfma_f32_32x32x16_bf16 v[80:95], v[84:87], v[136:139], 0
	v_add_f32_e32 v64, v191, v64
	v_add_f32_e32 v64, v194, v64
	v_add_f32_e32 v64, v190, v64
	v_add_f32_e32 v64, v192, v64
	v_add_f32_e32 v64, v169, v64
	v_add_f32_e32 v64, v171, v64
	s_waitcnt lgkmcnt(1)
	v_mfma_f32_32x32x16_bf16 v[96:111], v[198:201], v[140:143], v[96:111]
	v_add_f32_e32 v64, v167, v64
	v_add_f32_e32 v64, v170, v64
	v_add_f32_e32 v64, v165, v64
	v_add_f32_e32 v64, v168, v64
	v_add_f32_e32 v64, v164, v64
	v_add_f32_e32 v64, v166, v64
	v_exp_f32_e32 v239, v68
	s_waitcnt lgkmcnt(0)
	v_mfma_f32_32x32x16_bf16 v[80:95], v[202:205], v[140:143], v[80:95]
	ds_read_b128 v[198:201], v180 offset:16384
	ds_read_b128 v[202:205], v180 offset:24576
	v_add_f32_e32 v64, v238, v64
	v_exp_f32_e32 v240, v69
	v_exp_f32_e32 v241, v70
	v_exp_f32_e32 v242, v71
	s_waitcnt lgkmcnt(1)
	v_mfma_f32_32x32x16_bf16 v[96:111], v[198:201], v[132:135], v[96:111]
	ds_read_b128 v[198:201], v181 offset:16384
	ds_read_b128 v[206:209], v181 offset:24576
	ds_read_b128 v[210:213], v182 offset:16384
	ds_read_b128 v[214:217], v182 offset:24576
	ds_read_b128 v[218:221], v183 offset:16384
	ds_read_b128 v[222:225], v183 offset:24576
	v_exp_f32_e32 v243, v76
	v_exp_f32_e32 v244, v77
	v_exp_f32_e32 v245, v78
	v_exp_f32_e32 v79, v79
	s_waitcnt lgkmcnt(6)
	v_mfma_f32_32x32x16_bf16 v[80:95], v[202:205], v[132:135], v[80:95]
	ds_read_b128 v[202:205], v184 offset:16384
	ds_read_b128 v[226:229], v184 offset:24576
	ds_read_b128 v[230:233], v185 offset:16384
	ds_read_b128 v[234:237], v185 offset:24576
	s_waitcnt lgkmcnt(9)
	v_mfma_f32_32x32x16_bf16 v[96:111], v[198:201], v[128:131], v[96:111]
	v_exp_f32_e32 v199, v65
	v_exp_f32_e32 v200, v66
	v_exp_f32_e32 v201, v67
	v_add_f32_e32 v64, v199, v64
	v_add_f32_e32 v64, v200, v64
	v_add_f32_e32 v64, v201, v64
	s_waitcnt lgkmcnt(8)
	v_mfma_f32_32x32x16_bf16 v[80:95], v[206:209], v[128:131], v[80:95]
	v_exp_f32_e32 v206, v72
	v_add_f32_e32 v64, v239, v64
	v_exp_f32_e32 v207, v73
	v_add_f32_e32 v64, v240, v64
	v_exp_f32_e32 v208, v74
	v_add_f32_e32 v64, v241, v64
	v_exp_f32_e32 v209, v75
	s_waitcnt lgkmcnt(7)
	v_mfma_f32_32x32x16_bf16 v[96:111], v[210:213], v[124:127], v[96:111]
	v_add_f32_e32 v64, v242, v64
	v_add_f32_e32 v64, v206, v64
	v_add_f32_e32 v64, v207, v64
	v_add_f32_e32 v64, v208, v64
	v_add_f32_e32 v64, v209, v64
	v_add_f32_e32 v64, v243, v64
	v_add_f32_e32 v64, v244, v64
	s_waitcnt lgkmcnt(6)
	v_mfma_f32_32x32x16_bf16 v[80:95], v[214:217], v[124:127], v[80:95]
	v_add_f32_e32 v64, v245, v64
	v_add_f32_e32 v198, v79, v64
	v_cvt_pk_bf16_f32 v64, v196, v197
	v_cvt_pk_bf16_f32 v65, v193, v195
	v_cvt_pk_bf16_f32 v66, v191, v194
	v_cvt_pk_bf16_f32 v67, v190, v192
	s_waitcnt lgkmcnt(5)
	v_mfma_f32_32x32x16_bf16 v[96:111], v[218:221], v[120:123], v[96:111]
	v_cvt_pk_bf16_f32 v68, v169, v171
	v_cvt_pk_bf16_f32 v69, v167, v170
	v_cvt_pk_bf16_f32 v70, v165, v168
	v_cvt_pk_bf16_f32 v71, v164, v166
	v_cvt_pk_bf16_f32 v72, v238, v199
	v_cvt_pk_bf16_f32 v73, v200, v201
	v_cvt_pk_bf16_f32 v74, v239, v240
	s_waitcnt lgkmcnt(4)
	v_mfma_f32_32x32x16_bf16 v[80:95], v[222:225], v[120:123], v[80:95]
	v_cvt_pk_bf16_f32 v75, v241, v242
	v_cvt_pk_bf16_f32 v76, v206, v207
	v_cvt_pk_bf16_f32 v77, v208, v209
	v_cvt_pk_bf16_f32 v78, v243, v244
	v_cvt_pk_bf16_f32 v79, v245, v79
	s_waitcnt lgkmcnt(3)
	v_mfma_f32_32x32x16_bf16 v[96:111], v[202:205], v[116:119], v[96:111]
	s_add_i32 s33, s40, 0x8000
	s_and_b32 s43, s33, 0xc000
	ds_read_b64_tr_b16 v[190:191], v176
	ds_read_b64_tr_b16 v[192:193], v176 offset:2048
	ds_read_b64_tr_b16 v[194:195], v176 offset:4096
	ds_read_b64_tr_b16 v[196:197], v176 offset:6144
	s_waitcnt lgkmcnt(6)
	v_mfma_f32_32x32x16_bf16 v[80:95], v[226:229], v[116:119], v[80:95]
	ds_read_b64_tr_b16 v[200:201], v176 offset:8192
	ds_read_b64_tr_b16 v[202:203], v176 offset:10240
	ds_read_b64_tr_b16 v[204:205], v176 offset:12288
	ds_read_b64_tr_b16 v[206:207], v176 offset:14336
	s_add_i32 s74, s40, 0x4000
	s_and_b32 s74, s74, 0xc000
	s_add_u32 s98, s38, s22
	s_addc_u32 s99, s39, s23
	s_add_i32 s41, s67, s74
	s_add_u32 s100, s38, s24
	s_addc_u32 s101, s39, s25
	s_mov_b32 m0, s41
	s_add_i32 s74, s72, s74
	global_load_lds_dwordx4 v156, s[98:99]
	s_waitcnt lgkmcnt(9)
	v_mfma_f32_32x32x16_bf16 v[96:111], v[230:233], v[112:115], v[96:111]
	s_add_i32 m0, s41, 0x2000
	s_nop 0
	global_load_lds_dwordx4 v158, s[98:99]
	s_mov_b32 m0, s74
	s_nop 0
	global_load_lds_dwordx4 v162, s[100:101]
	s_waitcnt lgkmcnt(8)
	v_mfma_f32_32x32x16_bf16 v[80:95], v[234:237], v[112:115], v[80:95]
	s_add_i32 m0, s74, 0x2000
	s_nop 0
	global_load_lds_dwordx4 v160, s[100:101]
	s_nop 0
	s_waitcnt lgkmcnt(6)
	v_mfma_f32_32x32x16_bf16 v[48:63], v[64:67], v[190:193], v[48:63]
	v_exp_f32_e32 v232, v96
	ds_read_b64_tr_b16 v[190:191], v176 offset:512
	ds_read_b64_tr_b16 v[192:193], v176 offset:2560
	s_waitcnt lgkmcnt(6)
	v_mfma_f32_32x32x16_bf16 v[48:63], v[68:71], v[194:197], v[48:63]
	v_exp_f32_e32 v233, v97
	ds_read_b64_tr_b16 v[194:195], v176 offset:4608
	ds_read_b64_tr_b16 v[196:197], v176 offset:6656
	s_waitcnt lgkmcnt(6)
; #define SBAR() __builtin_amdgcn_sched_barrier(0)
; #define PUBLISH(n) do { asm volatile("s_waitcnt vmcnt(" #n ")" ::: "memory"); asm volatile("s_waitcnt lgkmcnt(0)" ::: "memory"); __builtin_amdgcn_s_barrier(); SBAR(); } while (0)
; template <int D0> __device__ __forceinline__ void pv_one(f32x16& od, int vb, bf16x8 pa0, bf16x8 pa1, bf16x8 pa2, bf16x8 pa3) {
;   const s16x4 l0 = tr_read<v_rd_off(D0, 0, 0)>(vb), h0 = tr_read<v_rd_off(D0, 0, 1)>(vb), l1 = tr_read<v_rd_off(D0, 1, 0)>(vb), h1 = tr_read<v_rd_off(D0, 1, 1)>(vb);
;   const s16x4 l2 = tr_read<v_rd_off(D0, 2, 0)>(vb), h2 = tr_read<v_rd_off(D0, 2, 1)>(vb), l3 = tr_read<v_rd_off(D0, 3, 0)>(vb), h3 = tr_read<v_rd_off(D0, 3, 1)>(vb);
;   asm volatile("s_waitcnt lgkmcnt(0)" ::: "memory"); SBAR();
;     ...
;   od = __builtin_amdgcn_mfma_f32_32x32x16_bf16(pa0, PK(l0, h0), od, 0, 0, 0);
;   od = __builtin_amdgcn_mfma_f32_32x32x16_bf16(pa1, PK(l1, h1), od, 0, 0, 0);
;   od = __builtin_amdgcn_mfma_f32_32x32x16_bf16(pa2, PK(l2, h2), od, 0, 0, 0);
;   od = __builtin_amdgcn_mfma_f32_32x32x16_bf16(pa3, PK(l3, h3), od, 0, 0, 0);
;     ...
; }
; __device__ __forceinline__ void pv_d0(f32x16* o, int vb, bf16x8 pa0, bf16x8 pa1, bf16x8 pa2, bf16x8 pa3) {
;   pv_one<0>(o[0], vb, pa0, pa1, pa2, pa3); pv_one<1>(o[1], vb, pa0, pa1, pa2, pa3); pv_one<2>(o[2], vb, pa0, pa1, pa2, pa3); pv_one<3>(o[3], vb, pa0, pa1, pa2, pa3);
; template <typename TQ> ...
;     ...
;     pv_d0(o, vb0 + ((j - 1) & 3) * (int)SHM_V, pa0, pa1, pa2, pa3); partialSM<true>(pB0, pB1, m_reg, mnB, alB);
;     PUBLISH(4);
;     SBAR(); qkt(pA0, pA1, (const bf16*)(K_lds + ((j + 1) & 3) * (int)SHM_K), qr, r32, hi);
;     finishSM(pB0, pB1, alB, l_reg, pa0, pa1, pa2, pa3); SBAR();
;     if (j + 3 < NT) { DMA_TILE(j + 3, (j + 3) & 3); } SBAR();
;     pv_d0(o, vb0 + (j & 3) * (int)SHM_V, pa0, pa1, pa2, pa3); partialSM<true>(pA0, pA1, m_reg, mnA, alA);
	v_mfma_f32_32x32x16_bf16 v[48:63], v[72:75], v[200:203], v[48:63]
	v_exp_f32_e32 v234, v98
	ds_read_b64_tr_b16 v[200:201], v176 offset:8704
	ds_read_b64_tr_b16 v[202:203], v176 offset:10752
	ds_read_b64_tr_b16 v[208:209], v176 offset:12800
	ds_read_b64_tr_b16 v[210:211], v176 offset:14848
	s_waitcnt lgkmcnt(8)
	v_mfma_f32_32x32x16_bf16 v[48:63], v[76:79], v[204:207], v[48:63]
	v_exp_f32_e32 v235, v99
	s_waitcnt lgkmcnt(6)
	v_mfma_f32_32x32x16_bf16 v[32:47], v[64:67], v[190:193], v[32:47]
	v_exp_f32_e32 v236, v100
	ds_read_b64_tr_b16 v[190:191], v176 offset:1024
	ds_read_b64_tr_b16 v[192:193], v176 offset:3072
	s_waitcnt lgkmcnt(6)
	v_mfma_f32_32x32x16_bf16 v[32:47], v[68:71], v[194:197], v[32:47]
	v_exp_f32_e32 v237, v101
	ds_read_b64_tr_b16 v[194:195], v176 offset:5120
	ds_read_b64_tr_b16 v[196:197], v176 offset:7168
	s_waitcnt lgkmcnt(6)
	v_mfma_f32_32x32x16_bf16 v[32:47], v[72:75], v[200:203], v[32:47]
	v_exp_f32_e32 v238, v102
	ds_read_b64_tr_b16 v[200:201], v176 offset:9216
	ds_read_b64_tr_b16 v[202:203], v176 offset:11264
	ds_read_b64_tr_b16 v[204:205], v176 offset:13312
	ds_read_b64_tr_b16 v[206:207], v176 offset:15360
	s_waitcnt lgkmcnt(8)
	v_mfma_f32_32x32x16_bf16 v[32:47], v[76:79], v[208:211], v[32:47]
	v_exp_f32_e32 v239, v103
	v_exp_f32_e32 v240, v104
	s_waitcnt lgkmcnt(6)
	v_mfma_f32_32x32x16_bf16 v[16:31], v[64:67], v[190:193], v[16:31]
	v_exp_f32_e32 v241, v105
	ds_read_b64_tr_b16 v[190:191], v176 offset:1536
	ds_read_b64_tr_b16 v[192:193], v176 offset:3584
	s_waitcnt lgkmcnt(6)
	v_mfma_f32_32x32x16_bf16 v[16:31], v[68:71], v[194:197], v[16:31]
	v_exp_f32_e32 v242, v106
	ds_read_b64_tr_b16 v[194:195], v176 offset:5632
	ds_read_b64_tr_b16 v[196:197], v176 offset:7680
	s_waitcnt lgkmcnt(6)
	v_mfma_f32_32x32x16_bf16 v[16:31], v[72:75], v[200:203], v[16:31]
	v_exp_f32_e32 v243, v107
	ds_read_b64_tr_b16 v[200:201], v176 offset:9728
	ds_read_b64_tr_b16 v[202:203], v176 offset:11776
	ds_read_b64_tr_b16 v[208:209], v176 offset:13824
	ds_read_b64_tr_b16 v[210:211], v176 offset:15872
	s_waitcnt lgkmcnt(8)
	v_mfma_f32_32x32x16_bf16 v[16:31], v[76:79], v[204:207], v[16:31]
	v_exp_f32_e32 v244, v108
	s_waitcnt lgkmcnt(6)
	v_mfma_f32_32x32x16_bf16 v[0:15], v[64:67], v[190:193], v[0:15]
	v_exp_f32_e32 v245, v109
	s_waitcnt lgkmcnt(4)
	v_mfma_f32_32x32x16_bf16 v[0:15], v[68:71], v[194:197], v[0:15]
	v_exp_f32_e32 v246, v110
	s_waitcnt lgkmcnt(2)
	v_mfma_f32_32x32x16_bf16 v[0:15], v[72:75], v[200:203], v[0:15]
	v_exp_f32_e32 v247, v111
	s_waitcnt vmcnt(4)
	s_waitcnt lgkmcnt(0)
	s_barrier
	v_mfma_f32_32x32x16_bf16 v[0:15], v[76:79], v[208:211], v[0:15]
	s_and_b32 s40, s40, 0xc000
	s_add_i32 s40, s57, s40
	ds_read_b128 v[64:67], v178 offset:32768
	ds_read_b128 v[68:71], v178 offset:40960
	ds_read_b128 v[190:193], v179 offset:32768
	ds_read_b128 v[194:197], v179 offset:40960
	s_waitcnt lgkmcnt(3)
	v_mfma_f32_32x32x16_bf16 v[96:111], v[64:67], v[136:139], 0
	v_exp_f32_e32 v80, v80
	v_exp_f32_e32 v81, v81
	v_exp_f32_e32 v82, v82
	v_exp_f32_e32 v83, v83
	v_exp_f32_e32 v87, v87
	v_exp_f32_e32 v248, v93
	v_exp_f32_e32 v249, v94
	s_waitcnt lgkmcnt(2)
	v_mfma_f32_32x32x16_bf16 v[64:79], v[68:71], v[136:139], 0
	s_waitcnt lgkmcnt(1)
	v_mfma_f32_32x32x16_bf16 v[96:111], v[190:193], v[140:143], v[96:111]
	s_waitcnt lgkmcnt(0)
	v_mfma_f32_32x32x16_bf16 v[64:79], v[194:197], v[140:143], v[64:79]
	ds_read_b128 v[190:193], v180 offset:32768
	ds_read_b128 v[194:197], v180 offset:40960
	s_waitcnt lgkmcnt(1)
	v_mfma_f32_32x32x16_bf16 v[96:111], v[190:193], v[132:135], v[96:111]
	ds_read_b128 v[190:193], v181 offset:32768
	ds_read_b128 v[200:203], v181 offset:40960
	ds_read_b128 v[204:207], v182 offset:32768
	ds_read_b128 v[208:211], v182 offset:40960
	ds_read_b128 v[212:215], v183 offset:32768
	ds_read_b128 v[216:219], v183 offset:40960
	s_waitcnt lgkmcnt(6)
	v_mfma_f32_32x32x16_bf16 v[64:79], v[194:197], v[132:135], v[64:79]
	ds_read_b128 v[194:197], v184 offset:32768
	ds_read_b128 v[220:223], v184 offset:40960
	ds_read_b128 v[224:227], v185 offset:32768
	ds_read_b128 v[228:231], v185 offset:40960
	s_waitcnt lgkmcnt(9)
	v_mfma_f32_32x32x16_bf16 v[96:111], v[190:193], v[128:131], v[96:111]
	s_cmp_ge_u32 s73, s37
	s_cselect_b64 s[40:41], -1, 0
	s_and_b64 vcc, exec, s[40:41]
	s_cbranch_vccnz .LBB0_463
	s_add_i32 s74, s67, s43
	s_add_u32 s98, s38, s26
	s_addc_u32 s99, s39, s27
	s_mov_b32 m0, s74
	s_add_i32 s43, s72, s43
	global_load_lds_dwordx4 v156, s[98:99]
	s_add_u32 s100, s38, s28
	s_addc_u32 s101, s39, s29
	s_add_i32 m0, s74, 0x2000
	s_nop 0
	global_load_lds_dwordx4 v158, s[98:99]
	s_mov_b32 m0, s43
	s_nop 0
	global_load_lds_dwordx4 v162, s[100:101]
	s_add_i32 m0, s43, 0x2000
	s_nop 0
	global_load_lds_dwordx4 v160, s[100:101]
; __device__ __forceinline__ void finishSM(f32x16& p0, f32x16& p1, float alpha, float& l_reg, bf16x8& pa0, bf16x8& pa1, bf16x8& pa2, bf16x8& pa3) {
;   for (int r = 0; r < 16; ++r) p1[r] = __builtin_amdgcn_exp2f(p1[r]);
;   float ps = 0; for (int r = 0; r < 16; ++r) ps += p0[r]; for (int r = 0; r < 16; ++r) ps += p1[r];
;   asm volatile("" : "+v"(ps));
;   l_reg = l_reg * alpha + ps;
;     ...
;   PK4(p0, 0, pa0); PK4(p0, 8, pa1); PK4(p1, 0, pa2); PK4(p1, 8, pa3);
;     ...
; }
; __device__ __forceinline__ void qkt(f32x16& p0, f32x16& p1, const bf16* Ks, const bf16x8* qr, int r32, int hi) {
;   p0 = f32x16{}; p1 = f32x16{};
;   for (int d0 = 0; d0 < 8; ++d0) { int cb = (d0 * 16 + hi * 8) * 2;
;     bf16x8 b0 = *reinterpret_cast<const bf16x8*>((const char*)Ks + KSWZ(r32, cb));
;     bf16x8 b1 = *reinterpret_cast<const bf16x8*>((const char*)Ks + KSWZ(32 + r32, cb));
;     p0 = __builtin_amdgcn_mfma_f32_32x32x16_bf16(b0, qr[d0], p0, 0, 0, 0);
;     p1 = __builtin_amdgcn_mfma_f32_32x32x16_bf16(b1, qr[d0], p1, 0, 0, 0); }
; }
; __device__ __forceinline__ int v_st(int k, int c) { const int kk = k;
;   return ((kk >> 3) * 4 + (c >> 5)) * 512 + ((kk & 7) * 32 + (c & 31)) * 2; }
; __device__ __forceinline__ int v_rd_base(int lane) { return ((lane & 3) << 3) | (((lane >> 2) & 3) << 6) | (((lane >> 4) & 1) << 5) | (((lane >> 5) & 1) << 8); }
; template <int OFF> __device__ __forceinline__ s16x4 tr_read(int vb) {
;   s16x4 r; asm volatile("ds_read_b64_tr_b16 %0, %1 offset:%2" : "=&v"(r) : "v"(vb), "i"(OFF) : "memory"); return r;
; }
; template <int D0> __device__ __forceinline__ void pv_one(f32x16& od, int vb, bf16x8 pa0, bf16x8 pa1, bf16x8 pa2, bf16x8 pa3) {
;   const s16x4 l0 = tr_read<v_rd_off(D0, 0, 0)>(vb), h0 = tr_read<v_rd_off(D0, 0, 1)>(vb), l1 = tr_read<v_rd_off(D0, 1, 0)>(vb), h1 = tr_read<v_rd_off(D0, 1, 1)>(vb);
;   const s16x4 l2 = tr_read<v_rd_off(D0, 2, 0)>(vb), h2 = tr_read<v_rd_off(D0, 2, 1)>(vb), l3 = tr_read<v_rd_off(D0, 3, 0)>(vb), h3 = tr_read<v_rd_off(D0, 3, 1)>(vb);
;   asm volatile("s_waitcnt lgkmcnt(0)" ::: "memory"); SBAR();
; template <typename TQ> ...
;     ...
;     finishSM(pB0, pB1, alB, l_reg, pa0, pa1, pa2, pa3); SBAR();
;     if (j + 3 < NT) { DMA_TILE(j + 3, (j + 3) & 3); } SBAR();
;     pv_d0(o, vb0 + (j & 3) * (int)SHM_V, pa0, pa1, pa2, pa3); partialSM<true>(pA0, pA1, m_reg, mnA, alA);
;     if (j + 3 < NT) { PUBLISH(4); } else { PUBLISH(0); }
.LBB0_463:
	v_exp_f32_e32 v190, v84
	v_add_f32_e32 v84, 0, v232
	v_add_f32_e32 v84, v233, v84
	v_add_f32_e32 v84, v234, v84
	v_add_f32_e32 v84, v235, v84
	v_add_f32_e32 v84, v236, v84
	v_add_f32_e32 v84, v237, v84
	s_waitcnt lgkmcnt(8)
	v_mfma_f32_32x32x16_bf16 v[64:79], v[200:203], v[128:131], v[64:79]
	v_add_f32_e32 v84, v238, v84
	v_add_f32_e32 v84, v239, v84
	v_add_f32_e32 v84, v240, v84
	v_add_f32_e32 v84, v241, v84
	v_add_f32_e32 v84, v242, v84
	v_add_f32_e32 v84, v243, v84
	v_add_f32_e32 v84, v244, v84
	s_waitcnt lgkmcnt(7)
	v_mfma_f32_32x32x16_bf16 v[96:111], v[204:207], v[124:127], v[96:111]
	v_add_f32_e32 v84, v245, v84
	v_add_f32_e32 v84, v246, v84
	v_add_f32_e32 v84, v247, v84
	v_add_f32_e32 v84, v80, v84
	v_exp_f32_e32 v191, v85
	v_add_f32_e32 v84, v81, v84
	v_exp_f32_e32 v192, v86
	s_waitcnt lgkmcnt(6)
	v_mfma_f32_32x32x16_bf16 v[64:79], v[208:211], v[124:127], v[64:79]
	v_add_f32_e32 v84, v82, v84
	v_add_f32_e32 v84, v83, v84
	v_exp_f32_e32 v193, v88
	v_add_f32_e32 v84, v190, v84
	v_exp_f32_e32 v200, v89
	v_add_f32_e32 v84, v191, v84
	v_exp_f32_e32 v201, v90
	s_waitcnt lgkmcnt(5)
	v_mfma_f32_32x32x16_bf16 v[96:111], v[212:215], v[120:123], v[96:111]
	v_add_f32_e32 v84, v192, v84
	v_exp_f32_e32 v202, v91
	v_add_f32_e32 v84, v87, v84
	v_exp_f32_e32 v203, v92
	v_add_f32_e32 v84, v193, v84
	v_add_f32_e32 v84, v200, v84
	v_add_f32_e32 v84, v201, v84
	s_waitcnt lgkmcnt(4)
	v_mfma_f32_32x32x16_bf16 v[64:79], v[216:219], v[120:123], v[64:79]
	v_exp_f32_e32 v204, v95
	v_add_f32_e32 v84, v202, v84
	v_add_f32_e32 v84, v203, v84
	v_add_f32_e32 v84, v248, v84
	v_add_f32_e32 v84, v249, v84
	v_add_f32_e32 v199, v204, v84
	s_waitcnt lgkmcnt(3)
	v_mfma_f32_32x32x16_bf16 v[96:111], v[194:197], v[116:119], v[96:111]
	v_cvt_pk_bf16_f32 v92, v232, v233
	v_cvt_pk_bf16_f32 v93, v234, v235
	v_cvt_pk_bf16_f32 v94, v236, v237
	v_cvt_pk_bf16_f32 v95, v238, v239
	v_cvt_pk_bf16_f32 v88, v240, v241
	v_cvt_pk_bf16_f32 v89, v242, v243
	v_cvt_pk_bf16_f32 v90, v244, v245
	s_waitcnt lgkmcnt(2)
	v_mfma_f32_32x32x16_bf16 v[64:79], v[220:223], v[116:119], v[64:79]
	v_cvt_pk_bf16_f32 v91, v246, v247
	v_cvt_pk_bf16_f32 v84, v80, v81
	v_cvt_pk_bf16_f32 v85, v82, v83
	v_cvt_pk_bf16_f32 v86, v190, v191
	v_cvt_pk_bf16_f32 v87, v192, v87
	v_cvt_pk_bf16_f32 v80, v193, v200
	v_cvt_pk_bf16_f32 v81, v201, v202
	ds_read_b64_tr_b16 v[164:165], v176 offset:16384
	ds_read_b64_tr_b16 v[166:167], v176 offset:18432
	ds_read_b64_tr_b16 v[168:169], v176 offset:20480
	ds_read_b64_tr_b16 v[170:171], v176 offset:22528
	s_waitcnt lgkmcnt(5)
	v_mfma_f32_32x32x16_bf16 v[96:111], v[224:227], v[112:115], v[96:111]
	v_cvt_pk_bf16_f32 v82, v203, v248
	v_cvt_pk_bf16_f32 v83, v249, v204
	ds_read_b64_tr_b16 v[190:191], v176 offset:24576
	ds_read_b64_tr_b16 v[192:193], v176 offset:26624
	ds_read_b64_tr_b16 v[194:195], v176 offset:28672
	ds_read_b64_tr_b16 v[196:197], v176 offset:30720
	s_waitcnt lgkmcnt(8)
	v_mfma_f32_32x32x16_bf16 v[64:79], v[228:231], v[112:115], v[64:79]
	s_nop 0
	s_waitcnt lgkmcnt(6)
	v_mfma_f32_32x32x16_bf16 v[48:63], v[92:95], v[164:167], v[48:63]
	ds_read_b64_tr_b16 v[164:165], v176 offset:16896
	ds_read_b64_tr_b16 v[166:167], v176 offset:18944
	s_waitcnt lgkmcnt(6)
	v_mfma_f32_32x32x16_bf16 v[48:63], v[88:91], v[168:171], v[48:63]
	ds_read_b64_tr_b16 v[168:169], v176 offset:20992
	ds_read_b64_tr_b16 v[170:171], v176 offset:23040
	s_waitcnt lgkmcnt(6)
	v_mfma_f32_32x32x16_bf16 v[48:63], v[84:87], v[190:193], v[48:63]
	ds_read_b64_tr_b16 v[190:191], v176 offset:25088
	ds_read_b64_tr_b16 v[192:193], v176 offset:27136
	ds_read_b64_tr_b16 v[200:201], v176 offset:29184
	ds_read_b64_tr_b16 v[202:203], v176 offset:31232
	s_waitcnt lgkmcnt(8)
	v_mfma_f32_32x32x16_bf16 v[48:63], v[80:83], v[194:197], v[48:63]
	s_waitcnt lgkmcnt(6)
	v_mfma_f32_32x32x16_bf16 v[32:47], v[92:95], v[164:167], v[32:47]
	ds_read_b64_tr_b16 v[164:165], v176 offset:17408
	ds_read_b64_tr_b16 v[166:167], v176 offset:19456
	s_waitcnt lgkmcnt(6)
	v_mfma_f32_32x32x16_bf16 v[32:47], v[88:91], v[168:171], v[32:47]
	ds_read_b64_tr_b16 v[168:169], v176 offset:21504
	ds_read_b64_tr_b16 v[170:171], v176 offset:23552
	s_waitcnt lgkmcnt(6)
	v_mfma_f32_32x32x16_bf16 v[32:47], v[84:87], v[190:193], v[32:47]
	ds_read_b64_tr_b16 v[190:191], v176 offset:25600
	ds_read_b64_tr_b16 v[192:193], v176 offset:27648
	ds_read_b64_tr_b16 v[194:195], v176 offset:29696
	ds_read_b64_tr_b16 v[196:197], v176 offset:31744
	s_waitcnt lgkmcnt(8)
	v_mfma_f32_32x32x16_bf16 v[32:47], v[80:83], v[200:203], v[32:47]
	s_waitcnt lgkmcnt(6)
	v_mfma_f32_32x32x16_bf16 v[16:31], v[92:95], v[164:167], v[16:31]
	ds_read_b64_tr_b16 v[164:165], v176 offset:17920
	ds_read_b64_tr_b16 v[166:167], v176 offset:19968
	s_waitcnt lgkmcnt(6)
	v_mfma_f32_32x32x16_bf16 v[16:31], v[88:91], v[168:171], v[16:31]
	ds_read_b64_tr_b16 v[168:169], v176 offset:22016
	ds_read_b64_tr_b16 v[170:171], v176 offset:24064
	s_waitcnt lgkmcnt(6)
	v_mfma_f32_32x32x16_bf16 v[16:31], v[84:87], v[190:193], v[16:31]
	ds_read_b64_tr_b16 v[190:191], v176 offset:26112
	ds_read_b64_tr_b16 v[192:193], v176 offset:28160
	ds_read_b64_tr_b16 v[200:201], v176 offset:30208
	ds_read_b64_tr_b16 v[202:203], v176 offset:32256
	s_waitcnt lgkmcnt(8)
	v_mfma_f32_32x32x16_bf16 v[16:31], v[80:83], v[194:197], v[16:31]
	s_waitcnt lgkmcnt(6)
	v_mfma_f32_32x32x16_bf16 v[0:15], v[92:95], v[164:167], v[0:15]
	s_mov_b64 s[42:43], -1
	s_and_b64 vcc, exec, s[40:41]
	s_waitcnt lgkmcnt(4)
	v_mfma_f32_32x32x16_bf16 v[0:15], v[88:91], v[168:171], v[0:15]
	s_waitcnt lgkmcnt(2)
	v_mfma_f32_32x32x16_bf16 v[0:15], v[84:87], v[190:193], v[0:15]
	s_waitcnt lgkmcnt(0)
	v_mfma_f32_32x32x16_bf16 v[0:15], v[80:83], v[200:203], v[0:15]
	s_cbranch_vccz .LBB0_465
	s_waitcnt vmcnt(0)
	s_barrier
	s_mov_b64 s[42:43], 0

; #define SBAR() __builtin_amdgcn_sched_barrier(0)
; #define PK4(P, BASE, OUT) do { u32x4 w = {cvtpk(P[BASE + 0], P[BASE + 1]), cvtpk(P[BASE + 2], P[BASE + 3]), cvtpk(P[BASE + 4], P[BASE + 5]), cvtpk(P[BASE + 6], P[BASE + 7])}; \
;     OUT = *reinterpret_cast<bf16x8*>(&w); } while (0)
; __device__ __forceinline__ void finishSM(f32x16& p0, f32x16& p1, float alpha, float& l_reg, bf16x8& pa0, bf16x8& pa1, bf16x8& pa2, bf16x8& pa3) {
;   for (int r = 0; r < 16; ++r) p1[r] = __builtin_amdgcn_exp2f(p1[r]);
;   float ps = 0; for (int r = 0; r < 16; ++r) ps += p0[r]; for (int r = 0; r < 16; ++r) ps += p1[r];
;   asm volatile("" : "+v"(ps));
;   l_reg = l_reg * alpha + ps;
;     ...
;   PK4(p0, 0, pa0); PK4(p0, 8, pa1); PK4(p1, 0, pa2); PK4(p1, 8, pa3);
;     ...
; }
; __device__ __forceinline__ void qkt(f32x16& p0, f32x16& p1, const bf16* Ks, const bf16x8* qr, int r32, int hi) {
;   p0 = f32x16{}; p1 = f32x16{};
;   for (int d0 = 0; d0 < 8; ++d0) { int cb = (d0 * 16 + hi * 8) * 2;
;     bf16x8 b0 = *reinterpret_cast<const bf16x8*>((const char*)Ks + KSWZ(r32, cb));
;     bf16x8 b1 = *reinterpret_cast<const bf16x8*>((const char*)Ks + KSWZ(32 + r32, cb));
;     p0 = __builtin_amdgcn_mfma_f32_32x32x16_bf16(b0, qr[d0], p0, 0, 0, 0);
;     p1 = __builtin_amdgcn_mfma_f32_32x32x16_bf16(b1, qr[d0], p1, 0, 0, 0); }
; template <typename TQ> ...
;     ...
;     SBAR(); qkt(pB0, pB1, (const bf16*)(K_lds + (j & 3) * (int)SHM_K), qr, r32, hi);
;     finishSM(pA0, pA1, alA, l_reg, pa0, pa1, pa2, pa3); SBAR();
;     DMA_TILE(j + 2, (j + 2) & 3); SBAR();
;     pv_d0(o, vb0 + ((j - 1) & 3) * (int)SHM_V, pa0, pa1, pa2, pa3); partialSM<true>(pB0, pB1, m_reg, mnB, alB);
.Lat461_b:
.Lat461_b_in:
	s_mov_b32 s40, s33
	s_addk_i32 s33, 0xc000
	s_and_b32 s42, s33, 0xc000
	s_add_i32 s33, s57, s42
	ds_read_b128 v[80:83], v178 offset:49152
	ds_read_b128 v[84:87], v178 offset:57344
	ds_read_b128 v[198:201], v179 offset:49152
	ds_read_b128 v[202:205], v179 offset:57344
	s_waitcnt lgkmcnt(3)
	v_mfma_f32_32x32x16_bf16 v[96:111], v[80:83], v[136:139], 0
	v_exp_f32_e32 v238, v64
	v_add_f32_e32 v64, 0, v196
	v_add_f32_e32 v64, v197, v64
	v_add_f32_e32 v64, v193, v64
	v_add_f32_e32 v64, v195, v64
	s_waitcnt lgkmcnt(2)
	v_mfma_f32_32x32x16_bf16 v[80:95], v[84:87], v[136:139], 0
	v_add_f32_e32 v64, v191, v64
	v_add_f32_e32 v64, v194, v64
	v_add_f32_e32 v64, v190, v64
	v_add_f32_e32 v64, v192, v64
	v_add_f32_e32 v64, v169, v64
	v_add_f32_e32 v64, v171, v64
	s_waitcnt lgkmcnt(1)
	v_mfma_f32_32x32x16_bf16 v[96:111], v[198:201], v[140:143], v[96:111]
	v_add_f32_e32 v64, v167, v64
	v_add_f32_e32 v64, v170, v64
	v_add_f32_e32 v64, v165, v64
	v_add_f32_e32 v64, v168, v64
	v_add_f32_e32 v64, v164, v64
	v_add_f32_e32 v64, v166, v64
	v_exp_f32_e32 v239, v68
	s_waitcnt lgkmcnt(0)
	v_mfma_f32_32x32x16_bf16 v[80:95], v[202:205], v[140:143], v[80:95]
	ds_read_b128 v[198:201], v180 offset:49152
	ds_read_b128 v[202:205], v180 offset:57344
	v_add_f32_e32 v64, v238, v64
	v_exp_f32_e32 v240, v69
	v_exp_f32_e32 v241, v70
	v_exp_f32_e32 v242, v71
	s_waitcnt lgkmcnt(1)
	v_mfma_f32_32x32x16_bf16 v[96:111], v[198:201], v[132:135], v[96:111]
	ds_read_b128 v[198:201], v181 offset:49152
	ds_read_b128 v[206:209], v181 offset:57344
	ds_read_b128 v[210:213], v182 offset:49152
	ds_read_b128 v[214:217], v182 offset:57344
	ds_read_b128 v[218:221], v183 offset:49152
	ds_read_b128 v[222:225], v183 offset:57344
	v_exp_f32_e32 v243, v76
	v_exp_f32_e32 v244, v77
	v_exp_f32_e32 v245, v78
	v_exp_f32_e32 v79, v79
	s_waitcnt lgkmcnt(6)
	v_mfma_f32_32x32x16_bf16 v[80:95], v[202:205], v[132:135], v[80:95]
	ds_read_b128 v[202:205], v184 offset:49152
	ds_read_b128 v[226:229], v184 offset:57344
	ds_read_b128 v[230:233], v185 offset:49152
	ds_read_b128 v[234:237], v185 offset:57344
	s_waitcnt lgkmcnt(9)
	v_mfma_f32_32x32x16_bf16 v[96:111], v[198:201], v[128:131], v[96:111]
	v_exp_f32_e32 v199, v65
	v_exp_f32_e32 v200, v66
	v_exp_f32_e32 v201, v67
	v_add_f32_e32 v64, v199, v64
	v_add_f32_e32 v64, v200, v64
	v_add_f32_e32 v64, v201, v64
	s_waitcnt lgkmcnt(8)
	v_mfma_f32_32x32x16_bf16 v[80:95], v[206:209], v[128:131], v[80:95]
	v_exp_f32_e32 v206, v72
	v_add_f32_e32 v64, v239, v64
	v_exp_f32_e32 v207, v73
	v_add_f32_e32 v64, v240, v64
	v_exp_f32_e32 v208, v74
	v_add_f32_e32 v64, v241, v64
	v_exp_f32_e32 v209, v75
	s_waitcnt lgkmcnt(7)
	v_mfma_f32_32x32x16_bf16 v[96:111], v[210:213], v[124:127], v[96:111]
	v_add_f32_e32 v64, v242, v64
	v_add_f32_e32 v64, v206, v64
	v_add_f32_e32 v64, v207, v64
	v_add_f32_e32 v64, v208, v64
	v_add_f32_e32 v64, v209, v64
	v_add_f32_e32 v64, v243, v64
	v_add_f32_e32 v64, v244, v64
	s_waitcnt lgkmcnt(6)
	v_mfma_f32_32x32x16_bf16 v[80:95], v[214:217], v[124:127], v[80:95]
	v_add_f32_e32 v64, v245, v64
	v_add_f32_e32 v198, v79, v64
	v_cvt_pk_bf16_f32 v64, v196, v197
	v_cvt_pk_bf16_f32 v65, v193, v195
	v_cvt_pk_bf16_f32 v66, v191, v194
	v_cvt_pk_bf16_f32 v67, v190, v192
	s_waitcnt lgkmcnt(5)
	v_mfma_f32_32x32x16_bf16 v[96:111], v[218:221], v[120:123], v[96:111]
	v_cvt_pk_bf16_f32 v68, v169, v171
	v_cvt_pk_bf16_f32 v69, v167, v170
	v_cvt_pk_bf16_f32 v70, v165, v168
	v_cvt_pk_bf16_f32 v71, v164, v166
	v_cvt_pk_bf16_f32 v72, v238, v199
	v_cvt_pk_bf16_f32 v73, v200, v201
	v_cvt_pk_bf16_f32 v74, v239, v240
	s_waitcnt lgkmcnt(4)
	v_mfma_f32_32x32x16_bf16 v[80:95], v[222:225], v[120:123], v[80:95]
	v_cvt_pk_bf16_f32 v75, v241, v242
	v_cvt_pk_bf16_f32 v76, v206, v207
	v_cvt_pk_bf16_f32 v77, v208, v209
	v_cvt_pk_bf16_f32 v78, v243, v244
	v_cvt_pk_bf16_f32 v79, v245, v79
	s_waitcnt lgkmcnt(3)
	v_mfma_f32_32x32x16_bf16 v[96:111], v[202:205], v[116:119], v[96:111]
	s_add_i32 s33, s40, 0x8000
	s_and_b32 s43, s33, 0xc000
	ds_read_b64_tr_b16 v[190:191], v176 offset:32768
	ds_read_b64_tr_b16 v[192:193], v176 offset:34816
	ds_read_b64_tr_b16 v[194:195], v176 offset:36864
	ds_read_b64_tr_b16 v[196:197], v176 offset:38912
	s_waitcnt lgkmcnt(6)
	v_mfma_f32_32x32x16_bf16 v[80:95], v[226:229], v[116:119], v[80:95]
	ds_read_b64_tr_b16 v[200:201], v176 offset:40960
	ds_read_b64_tr_b16 v[202:203], v176 offset:43008
	ds_read_b64_tr_b16 v[204:205], v176 offset:45056
	ds_read_b64_tr_b16 v[206:207], v176 offset:47104
	s_add_i32 s74, s40, 0x4000
	s_and_b32 s74, s74, 0xc000
	s_add_u32 s98, s38, s22
	s_addc_u32 s99, s39, s23
	s_add_i32 s41, s67, s74
	s_add_u32 s100, s38, s24
	s_addc_u32 s101, s39, s25
	s_mov_b32 m0, s41
	s_add_i32 s74, s72, s74
	global_load_lds_dwordx4 v156, s[98:99]
	s_waitcnt lgkmcnt(9)
	v_mfma_f32_32x32x16_bf16 v[96:111], v[230:233], v[112:115], v[96:111]
	s_add_i32 m0, s41, 0x2000
	s_nop 0
	global_load_lds_dwordx4 v158, s[98:99]
	s_mov_b32 m0, s74
	s_nop 0
	global_load_lds_dwordx4 v162, s[100:101]
	s_waitcnt lgkmcnt(8)
; #define SBAR() __builtin_amdgcn_sched_barrier(0)
; #define PUBLISH(n) do { asm volatile("s_waitcnt vmcnt(" #n ")" ::: "memory"); asm volatile("s_waitcnt lgkmcnt(0)" ::: "memory"); __builtin_amdgcn_s_barrier(); SBAR(); } while (0)
; template <int D0> __device__ __forceinline__ void pv_one(f32x16& od, int vb, bf16x8 pa0, bf16x8 pa1, bf16x8 pa2, bf16x8 pa3) {
;   const s16x4 l0 = tr_read<v_rd_off(D0, 0, 0)>(vb), h0 = tr_read<v_rd_off(D0, 0, 1)>(vb), l1 = tr_read<v_rd_off(D0, 1, 0)>(vb), h1 = tr_read<v_rd_off(D0, 1, 1)>(vb);
;   const s16x4 l2 = tr_read<v_rd_off(D0, 2, 0)>(vb), h2 = tr_read<v_rd_off(D0, 2, 1)>(vb), l3 = tr_read<v_rd_off(D0, 3, 0)>(vb), h3 = tr_read<v_rd_off(D0, 3, 1)>(vb);
;   asm volatile("s_waitcnt lgkmcnt(0)" ::: "memory"); SBAR();
;     ...
;   od = __builtin_amdgcn_mfma_f32_32x32x16_bf16(pa0, PK(l0, h0), od, 0, 0, 0);
;   od = __builtin_amdgcn_mfma_f32_32x32x16_bf16(pa1, PK(l1, h1), od, 0, 0, 0);
;   od = __builtin_amdgcn_mfma_f32_32x32x16_bf16(pa2, PK(l2, h2), od, 0, 0, 0);
;   od = __builtin_amdgcn_mfma_f32_32x32x16_bf16(pa3, PK(l3, h3), od, 0, 0, 0);
;     ...
; }
; __device__ __forceinline__ void pv_d0(f32x16* o, int vb, bf16x8 pa0, bf16x8 pa1, bf16x8 pa2, bf16x8 pa3) {
;   pv_one<0>(o[0], vb, pa0, pa1, pa2, pa3); pv_one<1>(o[1], vb, pa0, pa1, pa2, pa3); pv_one<2>(o[2], vb, pa0, pa1, pa2, pa3); pv_one<3>(o[3], vb, pa0, pa1, pa2, pa3);
; template <typename TQ> ...
;     ...
;     pv_d0(o, vb0 + ((j - 1) & 3) * (int)SHM_V, pa0, pa1, pa2, pa3); partialSM<true>(pB0, pB1, m_reg, mnB, alB);
;     PUBLISH(4);
;     SBAR(); qkt(pA0, pA1, (const bf16*)(K_lds + ((j + 1) & 3) * (int)SHM_K), qr, r32, hi);
;     finishSM(pB0, pB1, alB, l_reg, pa0, pa1, pa2, pa3); SBAR();
;     if (j + 3 < NT) { DMA_TILE(j + 3, (j + 3) & 3); } SBAR();
;     pv_d0(o, vb0 + (j & 3) * (int)SHM_V, pa0, pa1, pa2, pa3); partialSM<true>(pA0, pA1, m_reg, mnA, alA);
	v_mfma_f32_32x32x16_bf16 v[80:95], v[234:237], v[112:115], v[80:95]
	s_add_i32 m0, s74, 0x2000
	s_nop 0
	global_load_lds_dwordx4 v160, s[100:101]
	s_nop 0
	s_waitcnt lgkmcnt(6)
	v_mfma_f32_32x32x16_bf16 v[48:63], v[64:67], v[190:193], v[48:63]
	v_exp_f32_e32 v232, v96
	ds_read_b64_tr_b16 v[190:191], v176 offset:33280
	ds_read_b64_tr_b16 v[192:193], v176 offset:35328
	s_waitcnt lgkmcnt(6)
	v_mfma_f32_32x32x16_bf16 v[48:63], v[68:71], v[194:197], v[48:63]
	v_exp_f32_e32 v233, v97
	ds_read_b64_tr_b16 v[194:195], v176 offset:37376
	ds_read_b64_tr_b16 v[196:197], v176 offset:39424
	s_waitcnt lgkmcnt(6)
	v_mfma_f32_32x32x16_bf16 v[48:63], v[72:75], v[200:203], v[48:63]
	v_exp_f32_e32 v234, v98
	ds_read_b64_tr_b16 v[200:201], v176 offset:41472
	ds_read_b64_tr_b16 v[202:203], v176 offset:43520
	ds_read_b64_tr_b16 v[208:209], v176 offset:45568
	ds_read_b64_tr_b16 v[210:211], v176 offset:47616
	s_waitcnt lgkmcnt(8)
	v_mfma_f32_32x32x16_bf16 v[48:63], v[76:79], v[204:207], v[48:63]
	v_exp_f32_e32 v235, v99
	s_waitcnt lgkmcnt(6)
	v_mfma_f32_32x32x16_bf16 v[32:47], v[64:67], v[190:193], v[32:47]
	v_exp_f32_e32 v236, v100
	ds_read_b64_tr_b16 v[190:191], v176 offset:33792
	ds_read_b64_tr_b16 v[192:193], v176 offset:35840
	s_waitcnt lgkmcnt(6)
	v_mfma_f32_32x32x16_bf16 v[32:47], v[68:71], v[194:197], v[32:47]
	v_exp_f32_e32 v237, v101
	ds_read_b64_tr_b16 v[194:195], v176 offset:37888
	ds_read_b64_tr_b16 v[196:197], v176 offset:39936
	s_waitcnt lgkmcnt(6)
	v_mfma_f32_32x32x16_bf16 v[32:47], v[72:75], v[200:203], v[32:47]
	v_exp_f32_e32 v238, v102
	ds_read_b64_tr_b16 v[200:201], v176 offset:41984
	ds_read_b64_tr_b16 v[202:203], v176 offset:44032
	ds_read_b64_tr_b16 v[204:205], v176 offset:46080
	ds_read_b64_tr_b16 v[206:207], v176 offset:48128
	s_waitcnt lgkmcnt(8)
	v_mfma_f32_32x32x16_bf16 v[32:47], v[76:79], v[208:211], v[32:47]
	v_exp_f32_e32 v239, v103
	v_exp_f32_e32 v240, v104
	s_waitcnt lgkmcnt(6)
	v_mfma_f32_32x32x16_bf16 v[16:31], v[64:67], v[190:193], v[16:31]
	v_exp_f32_e32 v241, v105
	ds_read_b64_tr_b16 v[190:191], v176 offset:34304
	ds_read_b64_tr_b16 v[192:193], v176 offset:36352
	s_waitcnt lgkmcnt(6)
	v_mfma_f32_32x32x16_bf16 v[16:31], v[68:71], v[194:197], v[16:31]
	v_exp_f32_e32 v242, v106
	ds_read_b64_tr_b16 v[194:195], v176 offset:38400
	ds_read_b64_tr_b16 v[196:197], v176 offset:40448
	s_waitcnt lgkmcnt(6)
	v_mfma_f32_32x32x16_bf16 v[16:31], v[72:75], v[200:203], v[16:31]
	v_exp_f32_e32 v243, v107
	ds_read_b64_tr_b16 v[200:201], v176 offset:42496
	ds_read_b64_tr_b16 v[202:203], v176 offset:44544
	ds_read_b64_tr_b16 v[208:209], v176 offset:46592
	ds_read_b64_tr_b16 v[210:211], v176 offset:48640
	s_waitcnt lgkmcnt(8)
	v_mfma_f32_32x32x16_bf16 v[16:31], v[76:79], v[204:207], v[16:31]
	v_exp_f32_e32 v244, v108
	s_waitcnt lgkmcnt(6)
	v_mfma_f32_32x32x16_bf16 v[0:15], v[64:67], v[190:193], v[0:15]
	v_exp_f32_e32 v245, v109
	s_waitcnt lgkmcnt(4)
	v_mfma_f32_32x32x16_bf16 v[0:15], v[68:71], v[194:197], v[0:15]
	v_exp_f32_e32 v246, v110
	s_waitcnt lgkmcnt(2)
	v_mfma_f32_32x32x16_bf16 v[0:15], v[72:75], v[200:203], v[0:15]
	v_exp_f32_e32 v247, v111
	s_waitcnt vmcnt(4)
	s_waitcnt lgkmcnt(0)
	s_barrier
	v_mfma_f32_32x32x16_bf16 v[0:15], v[76:79], v[208:211], v[0:15]
	s_and_b32 s40, s40, 0xc000
	s_add_i32 s40, s57, s40
	ds_read_b128 v[64:67], v178
	ds_read_b128 v[68:71], v178 offset:8192
	ds_read_b128 v[190:193], v179
	ds_read_b128 v[194:197], v179 offset:8192
	s_waitcnt lgkmcnt(3)
	v_mfma_f32_32x32x16_bf16 v[96:111], v[64:67], v[136:139], 0
	v_exp_f32_e32 v80, v80
	v_exp_f32_e32 v81, v81
	v_exp_f32_e32 v82, v82
	v_exp_f32_e32 v83, v83
	v_exp_f32_e32 v87, v87
	v_exp_f32_e32 v248, v93
	v_exp_f32_e32 v249, v94
	s_waitcnt lgkmcnt(2)
	v_mfma_f32_32x32x16_bf16 v[64:79], v[68:71], v[136:139], 0
	s_waitcnt lgkmcnt(1)
	v_mfma_f32_32x32x16_bf16 v[96:111], v[190:193], v[140:143], v[96:111]
	s_waitcnt lgkmcnt(0)
	v_mfma_f32_32x32x16_bf16 v[64:79], v[194:197], v[140:143], v[64:79]
	ds_read_b128 v[190:193], v180
	ds_read_b128 v[194:197], v180 offset:8192
	s_waitcnt lgkmcnt(1)
	v_mfma_f32_32x32x16_bf16 v[96:111], v[190:193], v[132:135], v[96:111]
	ds_read_b128 v[190:193], v181
	ds_read_b128 v[200:203], v181 offset:8192
	ds_read_b128 v[204:207], v182
	ds_read_b128 v[208:211], v182 offset:8192
	ds_read_b128 v[212:215], v183
	ds_read_b128 v[216:219], v183 offset:8192
	s_waitcnt lgkmcnt(6)
	v_mfma_f32_32x32x16_bf16 v[64:79], v[194:197], v[132:135], v[64:79]
	ds_read_b128 v[194:197], v184
	ds_read_b128 v[220:223], v184 offset:8192
	ds_read_b128 v[224:227], v185
	ds_read_b128 v[228:231], v185 offset:8192
	s_waitcnt lgkmcnt(9)
	v_mfma_f32_32x32x16_bf16 v[96:111], v[190:193], v[128:131], v[96:111]
	s_cmp_ge_u32 s73, s37
	s_cselect_b64 s[40:41], -1, 0
	s_and_b64 vcc, exec, s[40:41]
	s_cbranch_vccnz .Lat463_b

; #define SBAR() __builtin_amdgcn_sched_barrier(0)
; #define PK4(P, BASE, OUT) do { u32x4 w = {cvtpk(P[BASE + 0], P[BASE + 1]), cvtpk(P[BASE + 2], P[BASE + 3]), cvtpk(P[BASE + 4], P[BASE + 5]), cvtpk(P[BASE + 6], P[BASE + 7])}; \
;     OUT = *reinterpret_cast<bf16x8*>(&w); } while (0)
; #define PUBLISH(n) do { asm volatile("s_waitcnt vmcnt(" #n ")" ::: "memory"); asm volatile("s_waitcnt lgkmcnt(0)" ::: "memory"); __builtin_amdgcn_s_barrier(); SBAR(); } while (0)
; __device__ __forceinline__ void finishSM(f32x16& p0, f32x16& p1, float alpha, float& l_reg, bf16x8& pa0, bf16x8& pa1, bf16x8& pa2, bf16x8& pa3) {
;   for (int r = 0; r < 16; ++r) p1[r] = __builtin_amdgcn_exp2f(p1[r]);
;   float ps = 0; for (int r = 0; r < 16; ++r) ps += p0[r]; for (int r = 0; r < 16; ++r) ps += p1[r];
;   asm volatile("" : "+v"(ps));
;   l_reg = l_reg * alpha + ps;
;     ...
;   PK4(p0, 0, pa0); PK4(p0, 8, pa1); PK4(p1, 0, pa2); PK4(p1, 8, pa3);
; template <typename TQ> ...
;     ...
;     SBAR(); qkt(pA0, pA1, (const bf16*)(K_lds + ((j + 1) & 3) * (int)SHM_K), qr, r32, hi);
;     finishSM(pB0, pB1, alB, l_reg, pa0, pa1, pa2, pa3); SBAR();
;     if (j + 3 < NT) { DMA_TILE(j + 3, (j + 3) & 3); } SBAR();
;     pv_d0(o, vb0 + (j & 3) * (int)SHM_V, pa0, pa1, pa2, pa3); partialSM<true>(pA0, pA1, m_reg, mnA, alA);
;     if (j + 3 < NT) { PUBLISH(4); } else { PUBLISH(0); }
	s_add_i32 s74, s67, s43
	s_add_u32 s98, s38, s26
	s_addc_u32 s99, s39, s27
	s_mov_b32 m0, s74
	s_add_i32 s43, s72, s43
	global_load_lds_dwordx4 v156, s[98:99]
	s_add_u32 s100, s38, s28
	s_addc_u32 s101, s39, s29
	s_add_i32 m0, s74, 0x2000
	s_nop 0
	global_load_lds_dwordx4 v158, s[98:99]
	s_mov_b32 m0, s43
	s_nop 0
	global_load_lds_dwordx4 v162, s[100:101]
	s_add_i32 m0, s43, 0x2000
	s_nop 0
	global_load_lds_dwordx4 v160, s[100:101]
.Lat463_b:
	v_exp_f32_e32 v190, v84
	v_add_f32_e32 v84, 0, v232
	v_add_f32_e32 v84, v233, v84
	v_add_f32_e32 v84, v234, v84
	v_add_f32_e32 v84, v235, v84
	v_add_f32_e32 v84, v236, v84
	v_add_f32_e32 v84, v237, v84
	s_waitcnt lgkmcnt(8)
	v_mfma_f32_32x32x16_bf16 v[64:79], v[200:203], v[128:131], v[64:79]
	v_add_f32_e32 v84, v238, v84
	v_add_f32_e32 v84, v239, v84
	v_add_f32_e32 v84, v240, v84
	v_add_f32_e32 v84, v241, v84
	v_add_f32_e32 v84, v242, v84
	v_add_f32_e32 v84, v243, v84
	v_add_f32_e32 v84, v244, v84
	s_waitcnt lgkmcnt(7)
	v_mfma_f32_32x32x16_bf16 v[96:111], v[204:207], v[124:127], v[96:111]
	v_add_f32_e32 v84, v245, v84
	v_add_f32_e32 v84, v246, v84
	v_add_f32_e32 v84, v247, v84
	v_add_f32_e32 v84, v80, v84
	v_exp_f32_e32 v191, v85
	v_add_f32_e32 v84, v81, v84
	v_exp_f32_e32 v192, v86
	s_waitcnt lgkmcnt(6)
	v_mfma_f32_32x32x16_bf16 v[64:79], v[208:211], v[124:127], v[64:79]
	v_add_f32_e32 v84, v82, v84
	v_add_f32_e32 v84, v83, v84
	v_exp_f32_e32 v193, v88
	v_add_f32_e32 v84, v190, v84
	v_exp_f32_e32 v200, v89
	v_add_f32_e32 v84, v191, v84
	v_exp_f32_e32 v201, v90
	s_waitcnt lgkmcnt(5)
	v_mfma_f32_32x32x16_bf16 v[96:111], v[212:215], v[120:123], v[96:111]
	v_add_f32_e32 v84, v192, v84
	v_exp_f32_e32 v202, v91
	v_add_f32_e32 v84, v87, v84
	v_exp_f32_e32 v203, v92
	v_add_f32_e32 v84, v193, v84
	v_add_f32_e32 v84, v200, v84
	v_add_f32_e32 v84, v201, v84
	s_waitcnt lgkmcnt(4)
	v_mfma_f32_32x32x16_bf16 v[64:79], v[216:219], v[120:123], v[64:79]
	v_exp_f32_e32 v204, v95
	v_add_f32_e32 v84, v202, v84
	v_add_f32_e32 v84, v203, v84
	v_add_f32_e32 v84, v248, v84
	v_add_f32_e32 v84, v249, v84
	v_add_f32_e32 v199, v204, v84
	s_waitcnt lgkmcnt(3)
	v_mfma_f32_32x32x16_bf16 v[96:111], v[194:197], v[116:119], v[96:111]
	v_cvt_pk_bf16_f32 v92, v232, v233
	v_cvt_pk_bf16_f32 v93, v234, v235
	v_cvt_pk_bf16_f32 v94, v236, v237
	v_cvt_pk_bf16_f32 v95, v238, v239
	v_cvt_pk_bf16_f32 v88, v240, v241
	v_cvt_pk_bf16_f32 v89, v242, v243
	v_cvt_pk_bf16_f32 v90, v244, v245
	s_waitcnt lgkmcnt(2)
	v_mfma_f32_32x32x16_bf16 v[64:79], v[220:223], v[116:119], v[64:79]
	v_cvt_pk_bf16_f32 v91, v246, v247
	v_cvt_pk_bf16_f32 v84, v80, v81
	v_cvt_pk_bf16_f32 v85, v82, v83
	v_cvt_pk_bf16_f32 v86, v190, v191
	v_cvt_pk_bf16_f32 v87, v192, v87
	v_cvt_pk_bf16_f32 v80, v193, v200
	v_cvt_pk_bf16_f32 v81, v201, v202
	ds_read_b64_tr_b16 v[164:165], v176 offset:49152
	ds_read_b64_tr_b16 v[166:167], v176 offset:51200
	ds_read_b64_tr_b16 v[168:169], v176 offset:53248
	ds_read_b64_tr_b16 v[170:171], v176 offset:55296
	s_waitcnt lgkmcnt(5)
	v_mfma_f32_32x32x16_bf16 v[96:111], v[224:227], v[112:115], v[96:111]
	v_cvt_pk_bf16_f32 v82, v203, v248
	v_cvt_pk_bf16_f32 v83, v249, v204
	ds_read_b64_tr_b16 v[190:191], v176 offset:57344
	ds_read_b64_tr_b16 v[192:193], v176 offset:59392
	ds_read_b64_tr_b16 v[194:195], v176 offset:61440
	ds_read_b64_tr_b16 v[196:197], v176 offset:63488
	s_waitcnt lgkmcnt(8)
	v_mfma_f32_32x32x16_bf16 v[64:79], v[228:231], v[112:115], v[64:79]
	s_nop 0
	s_waitcnt lgkmcnt(6)
	v_mfma_f32_32x32x16_bf16 v[48:63], v[92:95], v[164:167], v[48:63]
	ds_read_b64_tr_b16 v[164:165], v176 offset:49664
	ds_read_b64_tr_b16 v[166:167], v176 offset:51712
	s_waitcnt lgkmcnt(6)
	v_mfma_f32_32x32x16_bf16 v[48:63], v[88:91], v[168:171], v[48:63]
	ds_read_b64_tr_b16 v[168:169], v176 offset:53760
	ds_read_b64_tr_b16 v[170:171], v176 offset:55808
	s_waitcnt lgkmcnt(6)
	v_mfma_f32_32x32x16_bf16 v[48:63], v[84:87], v[190:193], v[48:63]
	ds_read_b64_tr_b16 v[190:191], v176 offset:57856
	ds_read_b64_tr_b16 v[192:193], v176 offset:59904
	ds_read_b64_tr_b16 v[200:201], v176 offset:61952
	ds_read_b64_tr_b16 v[202:203], v176 offset:64000
	s_waitcnt lgkmcnt(8)
	v_mfma_f32_32x32x16_bf16 v[48:63], v[80:83], v[194:197], v[48:63]
	s_waitcnt lgkmcnt(6)
	v_mfma_f32_32x32x16_bf16 v[32:47], v[92:95], v[164:167], v[32:47]
	ds_read_b64_tr_b16 v[164:165], v176 offset:50176
	ds_read_b64_tr_b16 v[166:167], v176 offset:52224
	s_waitcnt lgkmcnt(6)
	v_mfma_f32_32x32x16_bf16 v[32:47], v[88:91], v[168:171], v[32:47]
	ds_read_b64_tr_b16 v[168:169], v176 offset:54272
	ds_read_b64_tr_b16 v[170:171], v176 offset:56320
	s_waitcnt lgkmcnt(6)
	v_mfma_f32_32x32x16_bf16 v[32:47], v[84:87], v[190:193], v[32:47]
	ds_read_b64_tr_b16 v[190:191], v176 offset:58368
	ds_read_b64_tr_b16 v[192:193], v176 offset:60416
	ds_read_b64_tr_b16 v[194:195], v176 offset:62464
	ds_read_b64_tr_b16 v[196:197], v176 offset:64512
	s_waitcnt lgkmcnt(8)
	v_mfma_f32_32x32x16_bf16 v[32:47], v[80:83], v[200:203], v[32:47]
	s_waitcnt lgkmcnt(6)
	v_mfma_f32_32x32x16_bf16 v[16:31], v[92:95], v[164:167], v[16:31]
	ds_read_b64_tr_b16 v[164:165], v176 offset:50688
	ds_read_b64_tr_b16 v[166:167], v176 offset:52736
	s_waitcnt lgkmcnt(6)
	v_mfma_f32_32x32x16_bf16 v[16:31], v[88:91], v[168:171], v[16:31]
	ds_read_b64_tr_b16 v[168:169], v176 offset:54784
	ds_read_b64_tr_b16 v[170:171], v176 offset:56832
	s_waitcnt lgkmcnt(6)
	v_mfma_f32_32x32x16_bf16 v[16:31], v[84:87], v[190:193], v[16:31]
	ds_read_b64_tr_b16 v[190:191], v176 offset:58880
	ds_read_b64_tr_b16 v[192:193], v176 offset:60928
	ds_read_b64_tr_b16 v[200:201], v176 offset:62976
	ds_read_b64_tr_b16 v[202:203], v176 offset:65024
	s_waitcnt lgkmcnt(8)
	v_mfma_f32_32x32x16_bf16 v[16:31], v[80:83], v[194:197], v[16:31]
	s_waitcnt lgkmcnt(6)
	v_mfma_f32_32x32x16_bf16 v[0:15], v[92:95], v[164:167], v[0:15]
	s_mov_b64 s[42:43], -1
	s_and_b64 vcc, exec, s[40:41]
	s_waitcnt lgkmcnt(4)
	v_mfma_f32_32x32x16_bf16 v[0:15], v[88:91], v[168:171], v[0:15]
	s_waitcnt lgkmcnt(2)
	v_mfma_f32_32x32x16_bf16 v[0:15], v[84:87], v[190:193], v[0:15]
	s_waitcnt lgkmcnt(0)
	v_mfma_f32_32x32x16_bf16 v[0:15], v[80:83], v[200:203], v[0:15]
	s_cbranch_vccz .Lat465_b

; #define SBAR() __builtin_amdgcn_sched_barrier(0)
; #define PUBLISH(n) do { asm volatile("s_waitcnt vmcnt(" #n ")" ::: "memory"); asm volatile("s_waitcnt lgkmcnt(0)" ::: "memory"); __builtin_amdgcn_s_barrier(); SBAR(); } while (0)
; template <typename TQ> ...
;     ...
;     if (j + 3 < NT) { DMA_TILE(j + 3, (j + 3) & 3); } SBAR();
;     pv_d0(o, vb0 + (j & 3) * (int)SHM_V, pa0, pa1, pa2, pa3); partialSM<true>(pA0, pA1, m_reg, mnA, alA);
;     if (j + 3 < NT) { PUBLISH(4); } else { PUBLISH(0); }
	s_waitcnt vmcnt(0)
	s_barrier
	s_mov_b64 s[42:43], 0
.Lat465_b:
	s_andn2_b64 vcc, exec, s[42:43]
	s_cbranch_vccnz .LBB0_460

; #define SBAR() __builtin_amdgcn_sched_barrier(0)
; #define PUBLISH(n) do { asm volatile("s_waitcnt vmcnt(" #n ")" ::: "memory"); asm volatile("s_waitcnt lgkmcnt(0)" ::: "memory"); __builtin_amdgcn_s_barrier(); SBAR(); } while (0)
; template <typename TQ> ...
;     ...
;     if (j + 3 < NT) { PUBLISH(4); } else { PUBLISH(0); }
;   }
;   SBAR(); qkt(pB0, pB1, (const bf16*)(K_lds + ((NT - 1) & 3) * (int)SHM_K), qr, r32, hi);
;   finishSM(pA0, pA1, alA, l_reg, pa0, pa1, pa2, pa3); SBAR();
;   pv_d0(o, vb0 + ((NT - 2) & 3) * (int)SHM_V, pa0, pa1, pa2, pa3); partialSM<true>(pB0, pB1, m_reg, mnB, alB);
	s_waitcnt vmcnt(4)
	s_barrier
	s_branch .LBB0_460
.LBB0_467:
	v_add_u32_e32 v178, 0xffff0000, v178
	v_add_u32_e32 v179, 0xffff0000, v179
	v_add_u32_e32 v180, 0xffff0000, v180
	v_add_u32_e32 v181, 0xffff0000, v181
	v_add_u32_e32 v182, 0xffff0000, v182
	v_add_u32_e32 v183, 0xffff0000, v183
	v_add_u32_e32 v184, 0xffff0000, v184
	v_add_u32_e32 v185, 0xffff0000, v185
	s_and_b32 s33, s66, 0x3fffffc0
	s_lshl_b32 s33, s33, 2
	s_add_i32 s33, s33, 0
	s_add_i32 s33, s33, 0x20000
	v_add_u32_e32 v84, s60, v178
	ds_read_b128 v[80:83], v84
	ds_read_b128 v[84:87], v84 offset:8192
	v_add_u32_e32 v156, s60, v179
	v_add_u32_e32 v160, s60, v181
	v_exp_f32_e32 v218, v64
	s_waitcnt lgkmcnt(0)
	v_mfma_f32_32x32x16_bf16 v[96:111], v[80:83], v[136:139], 0
	v_add_f32_e32 v64, 0, v196
	v_add_f32_e32 v64, v197, v64
	v_add_f32_e32 v64, v193, v64
	v_add_u32_e32 v198, s60, v182
	v_add_f32_e32 v64, v195, v64
	v_add_f32_e32 v64, v191, v64
	v_add_f32_e32 v64, v194, v64
	v_mfma_f32_32x32x16_bf16 v[80:95], v[84:87], v[136:139], 0
	ds_read_b128 v[136:139], v156
	ds_read_b128 v[156:159], v156 offset:8192
	v_add_f32_e32 v64, v190, v64
	v_add_f32_e32 v64, v192, v64
	v_add_f32_e32 v64, v169, v64
	v_add_f32_e32 v64, v171, v64
	v_add_f32_e32 v64, v167, v64
	v_add_u32_e32 v206, s60, v183
	s_waitcnt lgkmcnt(0)
	v_mfma_f32_32x32x16_bf16 v[96:111], v[136:139], v[140:143], v[96:111]
	v_add_f32_e32 v64, v170, v64
	v_add_f32_e32 v64, v165, v64
	v_exp_f32_e32 v219, v65
	v_add_f32_e32 v64, v168, v64
	v_add_f32_e32 v64, v164, v64
	v_add_f32_e32 v64, v166, v64
	v_add_f32_e32 v64, v218, v64
	v_mfma_f32_32x32x16_bf16 v[80:95], v[156:159], v[140:143], v[80:95]
	v_add_u32_e32 v140, s60, v180
	ds_read_b128 v[136:139], v140
	ds_read_b128 v[140:143], v140 offset:8192
	ds_read_b128 v[156:159], v160
	ds_read_b128 v[160:163], v160 offset:8192
	v_add_f32_e32 v64, v219, v64
	v_exp_f32_e32 v220, v70
	v_add_u32_e32 v210, s60, v184
	v_exp_f32_e32 v221, v71
	s_waitcnt lgkmcnt(0)
	v_mfma_f32_32x32x16_bf16 v[96:111], v[136:139], v[132:135], v[96:111]
	ds_read_b128 v[136:139], v198
	ds_read_b128 v[198:201], v198 offset:8192
	ds_read_b128 v[202:205], v206
	ds_read_b128 v[206:209], v206 offset:8192
	v_exp_f32_e32 v222, v72
	v_add_u32_e32 v214, s60, v185
	v_exp_f32_e32 v79, v79
	v_mfma_f32_32x32x16_bf16 v[80:95], v[140:143], v[132:135], v[80:95]
	ds_read_b128 v[132:135], v210
	ds_read_b128 v[140:143], v210 offset:8192
	ds_read_b128 v[210:213], v214
	ds_read_b128 v[214:217], v214 offset:8192
	v_mfma_f32_32x32x16_bf16 v[96:111], v[156:159], v[128:131], v[96:111]
	v_exp_f32_e32 v156, v66
	v_exp_f32_e32 v157, v67
	v_exp_f32_e32 v158, v68
	v_exp_f32_e32 v159, v69
	v_add_f32_e32 v64, v156, v64
	v_add_f32_e32 v64, v157, v64
	v_add_f32_e32 v64, v158, v64
	v_mfma_f32_32x32x16_bf16 v[80:95], v[160:163], v[128:131], v[80:95]
	v_exp_f32_e32 v128, v73
	v_add_f32_e32 v64, v159, v64
	v_exp_f32_e32 v129, v74
	v_add_f32_e32 v64, v220, v64
	v_exp_f32_e32 v130, v75
	v_add_f32_e32 v64, v221, v64
	v_exp_f32_e32 v131, v76
	s_waitcnt lgkmcnt(0)
	v_mfma_f32_32x32x16_bf16 v[96:111], v[136:139], v[124:127], v[96:111]
	v_add_f32_e32 v64, v222, v64
	v_exp_f32_e32 v160, v77
	v_add_f32_e32 v64, v128, v64
	v_exp_f32_e32 v161, v78
	v_add_f32_e32 v64, v129, v64
	v_add_f32_e32 v64, v130, v64
	v_add_f32_e32 v64, v131, v64
	v_mfma_f32_32x32x16_bf16 v[80:95], v[198:201], v[124:127], v[80:95]
	v_add_f32_e32 v64, v160, v64
	v_add_f32_e32 v64, v161, v64
	v_add_f32_e32 v64, v79, v64
	v_mfma_f32_32x32x16_bf16 v[96:111], v[202:205], v[120:123], v[96:111]
	v_mfma_f32_32x32x16_bf16 v[80:95], v[206:209], v[120:123], v[80:95]
	v_mfma_f32_32x32x16_bf16 v[96:111], v[132:135], v[116:119], v[96:111]
	v_add_f32_e32 v132, v146, v64
	v_cvt_pk_bf16_f32 v64, v196, v197
	v_cvt_pk_bf16_f32 v65, v193, v195
	v_cvt_pk_bf16_f32 v66, v191, v194
	v_cvt_pk_bf16_f32 v67, v190, v192
	v_cvt_pk_bf16_f32 v68, v169, v171
	v_cvt_pk_bf16_f32 v69, v167, v170
	v_mfma_f32_32x32x16_bf16 v[80:95], v[140:143], v[116:119], v[80:95]
	v_cvt_pk_bf16_f32 v70, v165, v168
	v_cvt_pk_bf16_f32 v71, v164, v166
	v_cvt_pk_bf16_f32 v72, v218, v219
	v_cvt_pk_bf16_f32 v73, v156, v157
	v_cvt_pk_bf16_f32 v74, v158, v159
	v_cvt_pk_bf16_f32 v75, v220, v221
	v_cvt_pk_bf16_f32 v76, v222, v128
	v_mfma_f32_32x32x16_bf16 v[96:111], v[210:213], v[112:115], v[96:111]
	v_cvt_pk_bf16_f32 v77, v129, v130
	v_cvt_pk_bf16_f32 v78, v131, v160
	v_cvt_pk_bf16_f32 v79, v161, v79
	v_mfma_f32_32x32x16_bf16 v[80:95], v[214:217], v[112:115], v[80:95]
	ds_read_b64_tr_b16 v[112:113], v186 offset:0
	ds_read_b64_tr_b16 v[114:115], v186 offset:0x800
	ds_read_b64_tr_b16 v[116:117], v186 offset:0x1000
	ds_read_b64_tr_b16 v[118:119], v186 offset:0x1800
	ds_read_b64_tr_b16 v[120:121], v186 offset:0x2000
	ds_read_b64_tr_b16 v[122:123], v186 offset:0x2800
	ds_read_b64_tr_b16 v[124:125], v186 offset:0x3000
	ds_read_b64_tr_b16 v[126:127], v186 offset:0x3800
	s_waitcnt lgkmcnt(0)
	s_nop 0
	v_mfma_f32_32x32x16_bf16 v[48:63], v[64:67], v[112:115], v[48:63]
	ds_read_b64_tr_b16 v[112:113], v186 offset:0x200
	ds_read_b64_tr_b16 v[114:115], v186 offset:0xa00
	v_mfma_f32_32x32x16_bf16 v[48:63], v[68:71], v[116:119], v[48:63]
	ds_read_b64_tr_b16 v[116:117], v186 offset:0x1200
	ds_read_b64_tr_b16 v[118:119], v186 offset:0x1a00
	v_mfma_f32_32x32x16_bf16 v[48:63], v[72:75], v[120:123], v[48:63]
	ds_read_b64_tr_b16 v[120:121], v186 offset:0x2200
	ds_read_b64_tr_b16 v[122:123], v186 offset:0x2a00
	ds_read_b64_tr_b16 v[128:129], v186 offset:0x3200
	ds_read_b64_tr_b16 v[130:131], v186 offset:0x3a00
	s_waitcnt lgkmcnt(0)
; #define SBAR() __builtin_amdgcn_sched_barrier(0)
; template <typename TQ> ...
;     ...
;   pv_d0(o, vb0 + ((NT - 2) & 3) * (int)SHM_V, pa0, pa1, pa2, pa3); partialSM<true>(pB0, pB1, m_reg, mnB, alB);
;   finishSM(pB0, pB1, alB, l_reg, pa0, pa1, pa2, pa3); SBAR();
;   pv_d0(o, vb0 + ((NT - 1) & 3) * (int)SHM_V, pa0, pa1, pa2, pa3);
;   { auto rr = __builtin_amdgcn_permlane32_swap(__float_as_uint(l_reg), __float_as_uint(l_reg), false, false); l_reg = __uint_as_float(rr[0]) + __uint_as_float(rr[1]); }
;   if (hi == 0) li_l[r32] = l_reg; asm volatile("s_waitcnt lgkmcnt(0)" ::: "memory");
	v_mfma_f32_32x32x16_bf16 v[48:63], v[76:79], v[124:127], v[48:63]
	v_mfma_f32_32x32x16_bf16 v[32:47], v[64:67], v[112:115], v[32:47]
	ds_read_b64_tr_b16 v[112:113], v186 offset:0x400
	ds_read_b64_tr_b16 v[114:115], v186 offset:0xc00
	v_mfma_f32_32x32x16_bf16 v[32:47], v[68:71], v[116:119], v[32:47]
	ds_read_b64_tr_b16 v[116:117], v186 offset:0x1400
	ds_read_b64_tr_b16 v[118:119], v186 offset:0x1c00
	v_mfma_f32_32x32x16_bf16 v[32:47], v[72:75], v[120:123], v[32:47]
	ds_read_b64_tr_b16 v[120:121], v186 offset:0x2400
	ds_read_b64_tr_b16 v[122:123], v186 offset:0x2c00
	ds_read_b64_tr_b16 v[124:125], v186 offset:0x3400
	ds_read_b64_tr_b16 v[126:127], v186 offset:0x3c00
	s_waitcnt lgkmcnt(0)
	v_mfma_f32_32x32x16_bf16 v[32:47], v[76:79], v[128:131], v[32:47]
	v_mfma_f32_32x32x16_bf16 v[16:31], v[64:67], v[112:115], v[16:31]
	ds_read_b64_tr_b16 v[112:113], v186 offset:0x600
	ds_read_b64_tr_b16 v[114:115], v186 offset:0xe00
	v_mfma_f32_32x32x16_bf16 v[16:31], v[68:71], v[116:119], v[16:31]
	ds_read_b64_tr_b16 v[116:117], v186 offset:0x1600
	ds_read_b64_tr_b16 v[118:119], v186 offset:0x1e00
	v_mfma_f32_32x32x16_bf16 v[16:31], v[72:75], v[120:123], v[16:31]
	ds_read_b64_tr_b16 v[120:121], v186 offset:0x2600
	ds_read_b64_tr_b16 v[122:123], v186 offset:0x2e00
	ds_read_b64_tr_b16 v[128:129], v186 offset:0x3600
	ds_read_b64_tr_b16 v[130:131], v186 offset:0x3e00
	s_waitcnt lgkmcnt(0)
	v_mfma_f32_32x32x16_bf16 v[16:31], v[76:79], v[124:127], v[16:31]
	v_exp_f32_e32 v96, v96
	v_exp_f32_e32 v97, v97
	v_exp_f32_e32 v98, v98
	v_exp_f32_e32 v99, v99
	v_mfma_f32_32x32x16_bf16 v[0:15], v[64:67], v[112:115], v[0:15]
	v_exp_f32_e32 v100, v100
	v_add_f32_e32 v64, 0, v96
	v_exp_f32_e32 v101, v101
	v_add_f32_e32 v64, v97, v64
	v_exp_f32_e32 v65, v102
	v_add_f32_e32 v64, v98, v64
	v_exp_f32_e32 v102, v103
	v_add_f32_e32 v64, v99, v64
	v_exp_f32_e32 v103, v104
	v_add_f32_e32 v64, v100, v64
	v_exp_f32_e32 v104, v105
	v_add_f32_e32 v64, v101, v64
	v_exp_f32_e32 v105, v106
	v_add_f32_e32 v64, v65, v64
	v_exp_f32_e32 v106, v107
	v_mfma_f32_32x32x16_bf16 v[0:15], v[68:71], v[116:119], v[0:15]
	v_add_f32_e32 v64, v102, v64
	v_exp_f32_e32 v107, v108
	v_add_f32_e32 v64, v103, v64
	v_exp_f32_e32 v108, v109
	v_add_f32_e32 v64, v104, v64
	v_exp_f32_e32 v109, v110
	v_add_f32_e32 v64, v105, v64
	v_exp_f32_e32 v110, v111
	v_add_f32_e32 v64, v106, v64
	v_exp_f32_e32 v80, v80
	v_add_f32_e32 v64, v107, v64
	v_exp_f32_e32 v81, v81
	v_add_f32_e32 v64, v108, v64
	v_exp_f32_e32 v82, v82
	v_add_f32_e32 v64, v109, v64
	v_exp_f32_e32 v83, v83
	v_mfma_f32_32x32x16_bf16 v[0:15], v[72:75], v[120:123], v[0:15]
	v_add_f32_e32 v64, v110, v64
	v_exp_f32_e32 v84, v84
	v_add_f32_e32 v64, v80, v64
	v_exp_f32_e32 v85, v85
	v_add_f32_e32 v64, v81, v64
	v_exp_f32_e32 v86, v86
	v_add_f32_e32 v64, v82, v64
	v_exp_f32_e32 v87, v87
	v_add_f32_e32 v64, v83, v64
	v_exp_f32_e32 v88, v88
	v_add_f32_e32 v64, v84, v64
	v_exp_f32_e32 v89, v89
	v_add_f32_e32 v64, v85, v64
	v_exp_f32_e32 v90, v90
	v_add_f32_e32 v64, v86, v64
	v_mfma_f32_32x32x16_bf16 v[0:15], v[76:79], v[128:131], v[0:15]
	v_exp_f32_e32 v79, v91
	v_add_f32_e32 v64, v87, v64
	v_exp_f32_e32 v91, v92
	v_add_f32_e32 v64, v88, v64
	v_exp_f32_e32 v92, v93
	v_add_f32_e32 v64, v89, v64
	v_exp_f32_e32 v93, v94
	v_add_f32_e32 v64, v90, v64
	v_exp_f32_e32 v94, v95
	v_add_f32_e32 v64, v79, v64
	v_add_f32_e32 v64, v91, v64
	v_add_f32_e32 v64, v92, v64
	v_add_f32_e32 v64, v93, v64
	v_add_f32_e32 v64, v94, v64
	v_cvt_pk_bf16_f32 v66, v96, v97
	v_cvt_pk_bf16_f32 v67, v98, v99
	v_cvt_pk_bf16_f32 v68, v100, v101
	v_cvt_pk_bf16_f32 v69, v65, v102
	v_cvt_pk_bf16_f32 v70, v103, v104
	s_nop 0
	v_add_f32_e32 v64, v132, v64
	v_cvt_pk_bf16_f32 v71, v105, v106
	v_cvt_pk_bf16_f32 v72, v107, v108
	v_cvt_pk_bf16_f32 v73, v109, v110
	v_cvt_pk_bf16_f32 v74, v80, v81
	v_cvt_pk_bf16_f32 v75, v82, v83
	v_cvt_pk_bf16_f32 v76, v84, v85
	v_cvt_pk_bf16_f32 v77, v86, v87
	v_cvt_pk_bf16_f32 v78, v88, v89
	v_cvt_pk_bf16_f32 v79, v90, v79
	v_cvt_pk_bf16_f32 v80, v91, v92
	v_cvt_pk_bf16_f32 v81, v93, v94
	ds_read_b64_tr_b16 v[82:83], v187 offset:0
	ds_read_b64_tr_b16 v[84:85], v187 offset:0x800
	ds_read_b64_tr_b16 v[86:87], v187 offset:0x1000
	ds_read_b64_tr_b16 v[88:89], v187 offset:0x1800
	ds_read_b64_tr_b16 v[90:91], v187 offset:0x2000
	ds_read_b64_tr_b16 v[92:93], v187 offset:0x2800
	ds_read_b64_tr_b16 v[94:95], v187 offset:0x3000
	ds_read_b64_tr_b16 v[96:97], v187 offset:0x3800
	s_waitcnt lgkmcnt(0)
	s_nop 0
	v_mfma_f32_32x32x16_bf16 v[48:63], v[66:69], v[82:85], v[48:63]
	ds_read_b64_tr_b16 v[82:83], v187 offset:0x200
	ds_read_b64_tr_b16 v[84:85], v187 offset:0xa00
	v_mfma_f32_32x32x16_bf16 v[48:63], v[70:73], v[86:89], v[48:63]
	ds_read_b64_tr_b16 v[86:87], v187 offset:0x1200
	ds_read_b64_tr_b16 v[88:89], v187 offset:0x1a00
	v_mfma_f32_32x32x16_bf16 v[48:63], v[74:77], v[90:93], v[48:63]
	ds_read_b64_tr_b16 v[90:91], v187 offset:0x2200
	ds_read_b64_tr_b16 v[92:93], v187 offset:0x2a00
	ds_read_b64_tr_b16 v[98:99], v187 offset:0x3200
	ds_read_b64_tr_b16 v[100:101], v187 offset:0x3a00
	s_waitcnt lgkmcnt(0)
	v_mfma_f32_32x32x16_bf16 v[48:63], v[78:81], v[94:97], v[48:63]
	v_mfma_f32_32x32x16_bf16 v[32:47], v[66:69], v[82:85], v[32:47]
	ds_read_b64_tr_b16 v[82:83], v187 offset:0x400
	ds_read_b64_tr_b16 v[84:85], v187 offset:0xc00
	v_mfma_f32_32x32x16_bf16 v[32:47], v[70:73], v[86:89], v[32:47]
	ds_read_b64_tr_b16 v[86:87], v187 offset:0x1400
	ds_read_b64_tr_b16 v[88:89], v187 offset:0x1c00
	v_mfma_f32_32x32x16_bf16 v[32:47], v[74:77], v[90:93], v[32:47]
	ds_read_b64_tr_b16 v[90:91], v187 offset:0x2400
	ds_read_b64_tr_b16 v[92:93], v187 offset:0x2c00
	ds_read_b64_tr_b16 v[94:95], v187 offset:0x3400
	ds_read_b64_tr_b16 v[96:97], v187 offset:0x3c00
	s_waitcnt lgkmcnt(0)
	v_mfma_f32_32x32x16_bf16 v[32:47], v[78:81], v[98:101], v[32:47]
	v_mfma_f32_32x32x16_bf16 v[16:31], v[66:69], v[82:85], v[16:31]
	ds_read_b64_tr_b16 v[82:83], v187 offset:0x600
	ds_read_b64_tr_b16 v[84:85], v187 offset:0xe00
	v_mfma_f32_32x32x16_bf16 v[16:31], v[70:73], v[86:89], v[16:31]
	ds_read_b64_tr_b16 v[86:87], v187 offset:0x1600
	ds_read_b64_tr_b16 v[88:89], v187 offset:0x1e00
	v_mfma_f32_32x32x16_bf16 v[16:31], v[74:77], v[90:93], v[16:31]
	ds_read_b64_tr_b16 v[90:91], v187 offset:0x2600
	ds_read_b64_tr_b16 v[92:93], v187 offset:0x2e00
	ds_read_b64_tr_b16 v[98:99], v187 offset:0x3600
	ds_read_b64_tr_b16 v[100:101], v187 offset:0x3e00
	s_waitcnt lgkmcnt(0)
	v_mfma_f32_32x32x16_bf16 v[16:31], v[78:81], v[94:97], v[16:31]
	v_mfma_f32_32x32x16_bf16 v[0:15], v[66:69], v[82:85], v[0:15]
	v_mov_b32_e32 v65, v64
	s_nop 1
	v_permlane32_swap_b32_e32 v64, v65
	v_mfma_f32_32x32x16_bf16 v[0:15], v[70:73], v[86:89], v[0:15]
	v_mfma_f32_32x32x16_bf16 v[0:15], v[74:77], v[90:93], v[0:15]
	v_mfma_f32_32x32x16_bf16 v[0:15], v[78:81], v[98:101], v[0:15]
	s_and_saveexec_b64 s[38:39], s[2:3]
	s_cbranch_execz .LBB0_454
	v_lshl_add_u32 v66, v144, 2, s33
	v_add_f32_e32 v64, v64, v65
	ds_write_b32 v66, v64
	s_branch .LBB0_454

; __device__ __forceinline__ int v_rd_base(int lane) { return ((lane & 3) << 3) | (((lane >> 2) & 3) << 6) | (((lane >> 4) & 1) << 5) | (((lane >> 5) & 1) << 8); }
; #define PUBLISH(n) do { asm volatile("s_waitcnt vmcnt(" #n ")" ::: "memory"); asm volatile("s_waitcnt lgkmcnt(0)" ::: "memory"); __builtin_amdgcn_s_barrier(); SBAR(); } while (0)
; template <typename TQ> ...
;     ...
;   const int vb0 = (int)(uintptr_t)V_lds + v_rd_base(lane);
;   int koff[2], voff[2];
; #pragma unroll
;   for (int i = 0; i < 2; ++i) { const int P = wid * 1024 + lane * 16 + i * 8192;
;     { const int row = P >> 8, colB = (P & 255) ^ ((row & 7) << 4); koff[i] = row * LDK + (colB >> 1); }
;     { const int sub = P >> 9, k = (sub >> 2) * 8 + ((lane & 31) >> 2), c = (sub & 3) * 32 + (lane & 3) * 8; voff[i] = k * LDK + c; } }
;     ...
;   f32x16 pA0, pA1, pB0, pB1; float mnA, mnB, alA, alB; bf16x8 pa0, pa1, pa2, pa3; const int NT = seq / KVBLK;
;   DMA_TILE(0, 0); DMA_TILE(1, 1);
;   PUBLISH(4);
.LBB0_1363:
	s_or_b64 exec, exec, s[40:41]
	s_lshl_b64 s[38:39], s[38:39], 12
	s_add_u32 s40, s48, s38
	s_addc_u32 s41, s49, s39
	s_lshl_b32 s42, s42, 8
	s_add_u32 s40, s40, s42
	s_addc_u32 s41, s41, 0
	s_lshl_b32 s33, s33, 10
	v_cvt_pk_bf16_f32 v136, v64, v65
	v_cvt_pk_bf16_f32 v137, v62, v63
	v_cvt_pk_bf16_f32 v138, v60, v61
	v_cvt_pk_bf16_f32 v139, v58, v59
	v_cvt_pk_bf16_f32 v140, v56, v57
	v_cvt_pk_bf16_f32 v141, v54, v55
	v_cvt_pk_bf16_f32 v142, v52, v53
	v_cvt_pk_bf16_f32 v143, v50, v51
	v_cvt_pk_bf16_f32 v132, v48, v49
	v_cvt_pk_bf16_f32 v133, v46, v47
	v_cvt_pk_bf16_f32 v134, v44, v45
	v_cvt_pk_bf16_f32 v135, v42, v43
	v_cvt_pk_bf16_f32 v128, v40, v41
	v_cvt_pk_bf16_f32 v129, v38, v39
	v_cvt_pk_bf16_f32 v130, v36, v37
	v_cvt_pk_bf16_f32 v131, v34, v35
	v_cvt_pk_bf16_f32 v124, v32, v33
	v_cvt_pk_bf16_f32 v125, v30, v31
	v_cvt_pk_bf16_f32 v126, v28, v29
	v_cvt_pk_bf16_f32 v127, v26, v27
	v_cvt_pk_bf16_f32 v120, v24, v25
	v_cvt_pk_bf16_f32 v121, v22, v23
	v_cvt_pk_bf16_f32 v122, v20, v21
	v_cvt_pk_bf16_f32 v123, v18, v19
	v_cvt_pk_bf16_f32 v116, v16, v17
	v_cvt_pk_bf16_f32 v117, v14, v15
	v_cvt_pk_bf16_f32 v118, v12, v13
	v_cvt_pk_bf16_f32 v119, v10, v11
	v_cvt_pk_bf16_f32 v112, v8, v9
	v_cvt_pk_bf16_f32 v113, v6, v7
	v_cvt_pk_bf16_f32 v114, v4, v5
	v_cvt_pk_bf16_f32 v115, v0, v1
	v_or_b32_e32 v1, s33, v172
	v_lshrrev_b32_e32 v0, 4, v1
	v_ashrrev_i32_e32 v2, 8, v1
	v_and_b32_e32 v36, 0x60, v0
	v_lshlrev_b32_e32 v0, 4, v2
	v_add_u32_e32 v1, 0x2000, v1
	v_bitop3_b32 v0, v0, v173, s45 bitop3:0x6c
	v_ashrrev_i32_e32 v1, 8, v1
	v_lshlrev_b32_e32 v37, 11, v2
	v_lshrrev_b32_e32 v0, 1, v0
	v_lshlrev_b32_e32 v4, 4, v1
	v_or_b32_e32 v3, v36, v175
	v_or_b32_e32 v0, v0, v37
	v_bitop3_b32 v4, v4, v173, s45 bitop3:0x6c
	v_lshlrev_b32_e32 v38, 11, v1
	v_and_or_b32 v1, v1, s55, v174
	v_lshrrev_b32_e32 v4, 1, v4
	v_lshl_or_b32 v6, v1, 11, v3
	v_ashrrev_i32_e32 v1, 31, v0
	v_or_b32_e32 v4, v4, v38
	v_lshlrev_b64 v[156:157], 1, v[0:1]
	v_and_or_b32 v2, v2, s55, v174
	v_lshl_add_u64 v[0:1], s[40:41], 0, v[156:157]
	s_add_i32 s66, s56, s33
	v_ashrrev_i32_e32 v5, 31, v4
	v_lshl_or_b32 v2, v2, 11, v3
	v_lshl_add_u64 v[0:1], v[0:1], 0, s[16:17]
	s_mov_b32 m0, s66
	v_lshlrev_b64 v[158:159], 1, v[4:5]
	global_load_lds_dwordx4 v[0:1], off
	v_lshl_add_u64 v[0:1], s[40:41], 0, v[158:159]
	s_add_i32 s67, s33, 0
	v_ashrrev_i32_e32 v3, 31, v2
	v_lshl_add_u64 v[0:1], v[0:1], 0, s[16:17]
	s_add_i32 m0, s67, 0x12000
	v_lshlrev_b64 v[32:33], 1, v[2:3]
	global_load_lds_dwordx4 v[0:1], off
	v_lshl_add_u64 v[0:1], s[40:41], 0, v[32:33]
	v_lshl_add_u64 v[0:1], v[0:1], 0, s[18:19]
	s_mov_b32 m0, s67
	v_ashrrev_i32_e32 v7, 31, v6
	global_load_lds_dwordx4 v[0:1], off
	s_add_i32 m0, s67, 0x2000
	v_lshlrev_b64 v[34:35], 1, v[6:7]
	s_add_u32 s72, s40, 0x40c00
	v_lshl_add_u64 v[0:1], s[40:41], 0, v[34:35]
	s_addc_u32 s73, s41, 0
	v_lshl_add_u64 v[0:1], v[0:1], 0, s[18:19]
	s_add_u32 s74, s40, 0x40e00
	global_load_lds_dwordx4 v[0:1], off
	s_addc_u32 s75, s41, 0
	v_lshl_add_u64 v[0:1], s[72:73], 0, v[156:157]
	s_add_i32 m0, s67, 0x14000
	s_nop 0
	global_load_lds_dwordx4 v[0:1], off
	v_lshl_add_u64 v[0:1], s[72:73], 0, v[158:159]
	s_add_i32 m0, s67, 0x16000
	s_mov_b32 s72, 4
	global_load_lds_dwordx4 v[0:1], off
	v_lshl_add_u64 v[0:1], s[74:75], 0, v[32:33]
	s_add_i32 m0, s67, 0x4000
	s_nop 0
	global_load_lds_dwordx4 v[0:1], off
	v_lshl_add_u64 v[0:1], s[74:75], 0, v[34:35]
	s_add_i32 m0, s67, 0x6000
	s_nop 0
	global_load_lds_dwordx4 v[0:1], off
	s_waitcnt vmcnt(4)
	s_waitcnt lgkmcnt(0)
	s_barrier
; #define SBAR() __builtin_amdgcn_sched_barrier(0)
; #define PUBLISH(n) do { asm volatile("s_waitcnt vmcnt(" #n ")" ::: "memory"); asm volatile("s_waitcnt lgkmcnt(0)" ::: "memory"); __builtin_amdgcn_s_barrier(); SBAR(); } while (0)
; template <typename TQ> ...
;     ...
;   DMA_TILE(0, 0); DMA_TILE(1, 1);
;   PUBLISH(4);
;   qkt(pA0, pA1, (const bf16*)K_lds, qr, r32, hi); partialSM<true>(pA0, pA1, m_reg, mnA, alA);
;   DMA_TILE(2, 2);
;   PUBLISH(4);
;   for (int j = 1; j + 1 < NT; j += 2) {
;     SBAR(); qkt(pB0, pB1, (const bf16*)(K_lds + (j & 3) * (int)SHM_K), qr, r32, hi);
	v_add_u32_e32 v4, s56, v178
	ds_read_b128 v[0:3], v4
	ds_read_b128 v[16:19], v4 offset:8192
	v_add_u32_e32 v20, s56, v179
	v_add_u32_e32 v24, s56, v184
	s_add_u32 s74, s40, 0x80c00
	s_waitcnt lgkmcnt(0)
	v_mfma_f32_32x32x16_bf16 v[0:15], v[0:3], v[136:139], 0
	s_addc_u32 s75, s41, 0
	s_add_u32 s40, s40, 0x80e00
	v_add_u32_e32 v28, s56, v185
	s_addc_u32 s41, s41, 0
	s_add_i32 m0, s67, 0x18000
	s_mov_b32 s33, 0x8000
	v_mfma_f32_32x32x16_bf16 v[64:79], v[16:19], v[136:139], 0
	ds_read_b128 v[16:19], v20
	ds_read_b128 v[20:23], v20 offset:8192
	s_waitcnt lgkmcnt(0)
	v_mfma_f32_32x32x16_bf16 v[0:15], v[16:19], v[140:143], v[0:15]
	v_mfma_f32_32x32x16_bf16 v[64:79], v[20:23], v[140:143], v[64:79]
	v_add_u32_e32 v20, s56, v180
	ds_read_b128 v[16:19], v20
	ds_read_b128 v[20:23], v20 offset:8192
	s_waitcnt lgkmcnt(0)
	v_mfma_f32_32x32x16_bf16 v[0:15], v[16:19], v[132:135], v[0:15]
	v_mfma_f32_32x32x16_bf16 v[64:79], v[20:23], v[132:135], v[64:79]
	v_add_u32_e32 v20, s56, v181
	ds_read_b128 v[16:19], v20
	ds_read_b128 v[20:23], v20 offset:8192
	s_waitcnt lgkmcnt(0)
	v_mfma_f32_32x32x16_bf16 v[0:15], v[16:19], v[128:131], v[0:15]
	v_mfma_f32_32x32x16_bf16 v[64:79], v[20:23], v[128:131], v[64:79]
	v_add_u32_e32 v20, s56, v182
	ds_read_b128 v[16:19], v20
	ds_read_b128 v[20:23], v20 offset:8192
	s_waitcnt lgkmcnt(0)
	v_mfma_f32_32x32x16_bf16 v[0:15], v[16:19], v[124:127], v[0:15]
	v_mfma_f32_32x32x16_bf16 v[64:79], v[20:23], v[124:127], v[64:79]
	v_add_u32_e32 v20, s56, v183
	ds_read_b128 v[16:19], v20
	ds_read_b128 v[20:23], v20 offset:8192
	s_waitcnt lgkmcnt(0)
	v_mfma_f32_32x32x16_bf16 v[0:15], v[16:19], v[120:123], v[0:15]
	v_mfma_f32_32x32x16_bf16 v[64:79], v[20:23], v[120:123], v[64:79]
	ds_read_b128 v[16:19], v24
	ds_read_b128 v[20:23], v24 offset:8192
	ds_read_b128 v[24:27], v28
	ds_read_b128 v[28:31], v28 offset:8192
	s_waitcnt lgkmcnt(0)
	v_mfma_f32_32x32x16_bf16 v[0:15], v[16:19], v[116:119], v[0:15]
	v_lshl_add_u64 v[16:17], s[74:75], 0, v[156:157]
	global_load_lds_dwordx4 v[16:17], off
	v_lshl_add_u64 v[16:17], s[74:75], 0, v[158:159]
	s_add_i32 m0, s67, 0x1a000
	s_nop 0
	global_load_lds_dwordx4 v[16:17], off
	v_lshl_add_u64 v[16:17], s[40:41], 0, v[32:33]
	s_add_i32 m0, s67, 0x8000
	v_mfma_f32_32x32x16_bf16 v[64:79], v[20:23], v[116:119], v[64:79]
	global_load_lds_dwordx4 v[16:17], off
	v_lshl_add_u64 v[16:17], s[40:41], 0, v[34:35]
	s_add_i32 m0, s67, 0xa000
	s_nop 0
	global_load_lds_dwordx4 v[16:17], off
	v_mfma_f32_32x32x16_bf16 v[0:15], v[24:27], v[112:115], v[0:15]
	s_waitcnt vmcnt(4)
	s_waitcnt lgkmcnt(0)
	s_barrier
	v_mfma_f32_32x32x16_bf16 v[64:79], v[28:31], v[112:115], v[64:79]
	s_nop 9
	v_exp_f32_e32 v196, v0
	v_and_or_b32 v0, v38, s58, v188
	v_add_u32_e32 v0, v0, v36
	v_exp_f32_e32 v197, v1
	v_ashrrev_i32_e32 v1, 31, v0
	v_exp_f32_e32 v193, v2
	v_exp_f32_e32 v195, v3
	v_exp_f32_e32 v191, v4
	v_exp_f32_e32 v194, v5
	v_exp_f32_e32 v190, v6
	v_exp_f32_e32 v192, v7
	v_exp_f32_e32 v169, v8
	v_exp_f32_e32 v171, v9
	v_exp_f32_e32 v167, v10
	v_exp_f32_e32 v170, v11
	v_exp_f32_e32 v165, v12
	v_exp_f32_e32 v168, v13
	v_exp_f32_e32 v164, v14
	v_exp_f32_e32 v166, v15
	v_lshlrev_b64 v[160:161], 1, v[0:1]
	v_and_or_b32 v0, v37, s58, v188
	s_or_b32 s38, s38, s42
	v_add_u32_e32 v0, v0, v36
	s_add_u32 s38, s8, s38
	v_ashrrev_i32_e32 v1, 31, v0
	v_mov_b32_e32 v146, 0
	s_addc_u32 s39, s9, s39
	v_lshlrev_b64 v[162:163], 1, v[0:1]
	v_mov_b32_e32 v0, 0
	v_mov_b32_e32 v1, v146
	v_mov_b32_e32 v2, v146
	v_mov_b32_e32 v3, v146
	v_mov_b32_e32 v4, v146
	v_mov_b32_e32 v5, v146
	v_mov_b32_e32 v6, v146
	v_mov_b32_e32 v7, v146
	v_mov_b32_e32 v8, v146
	v_mov_b32_e32 v9, v146
	v_mov_b32_e32 v10, v146
	v_mov_b32_e32 v11, v146
	v_mov_b32_e32 v12, v146
	v_mov_b32_e32 v13, v146
	v_mov_b32_e32 v14, v146
	v_mov_b32_e32 v15, v146
	v_mov_b32_e32 v16, 0
	v_mov_b32_e32 v17, v146
	v_mov_b32_e32 v18, v146
	v_mov_b32_e32 v19, v146
	v_mov_b32_e32 v20, v146
	v_mov_b32_e32 v21, v146
	v_mov_b32_e32 v22, v146
	v_mov_b32_e32 v23, v146
	v_mov_b32_e32 v24, v146
	v_mov_b32_e32 v25, v146
	v_mov_b32_e32 v26, v146
	v_mov_b32_e32 v27, v146
	v_mov_b32_e32 v28, v146
	v_mov_b32_e32 v29, v146
	v_mov_b32_e32 v30, v146
	v_mov_b32_e32 v31, v146
	v_mov_b32_e32 v32, 0
	v_mov_b32_e32 v33, v146
	v_mov_b32_e32 v34, v146
	v_mov_b32_e32 v35, v146
	v_mov_b32_e32 v36, v146
	v_mov_b32_e32 v37, v146
	v_mov_b32_e32 v38, v146
	v_mov_b32_e32 v39, v146
	v_mov_b32_e32 v40, v146
	v_mov_b32_e32 v41, v146
	v_mov_b32_e32 v42, v146
	v_mov_b32_e32 v43, v146
	v_mov_b32_e32 v44, v146
	v_mov_b32_e32 v45, v146
	v_mov_b32_e32 v46, v146
	v_mov_b32_e32 v47, v146
	v_mov_b32_e32 v48, 0
	v_mov_b32_e32 v49, v146
	v_mov_b32_e32 v50, v146
	v_mov_b32_e32 v51, v146
	v_mov_b32_e32 v52, v146
	v_mov_b32_e32 v53, v146
	v_mov_b32_e32 v54, v146
	v_mov_b32_e32 v55, v146
	v_mov_b32_e32 v56, v146
	v_mov_b32_e32 v57, v146
	v_mov_b32_e32 v58, v146
	v_mov_b32_e32 v59, v146
	v_mov_b32_e32 v60, v146
	v_mov_b32_e32 v61, v146
	v_mov_b32_e32 v62, v146
	v_mov_b32_e32 v63, v146
	v_add_u32_e32 v178, 0x10000, v178
	v_add_u32_e32 v179, 0x10000, v179
	v_add_u32_e32 v180, 0x10000, v180
	v_add_u32_e32 v181, 0x10000, v181
	v_add_u32_e32 v182, 0x10000, v182
	v_add_u32_e32 v183, 0x10000, v183
	v_add_u32_e32 v184, 0x10000, v184
	v_add_u32_e32 v185, 0x10000, v185
	s_branch .LBB0_1365

; #define SBAR() __builtin_amdgcn_sched_barrier(0)
; template <typename TQ> ...
;     ...
;   for (int j = 1; j + 1 < NT; j += 2) {
;     SBAR(); qkt(pB0, pB1, (const bf16*)(K_lds + (j & 3) * (int)SHM_K), qr, r32, hi);
;     finishSM(pA0, pA1, alA, l_reg, pa0, pa1, pa2, pa3); SBAR();
;     DMA_TILE(j + 2, (j + 2) & 3); SBAR();
;     pv_d0(o, vb0 + ((j - 1) & 3) * (int)SHM_V, pa0, pa1, pa2, pa3); partialSM<true>(pB0, pB1, m_reg, mnB, alB);
.LBB0_1365:
	s_bitcmp1_b32 s72, 1
	s_cbranch_scc1 .Lat1365_b_in
	s_mov_b32 s40, s33
	s_addk_i32 s33, 0xc000
	s_and_b32 s42, s33, 0xc000
	s_add_i32 s33, s56, s42
	ds_read_b128 v[80:83], v178 offset:16384
	ds_read_b128 v[84:87], v178 offset:24576
	ds_read_b128 v[198:201], v179 offset:16384
	ds_read_b128 v[202:205], v179 offset:24576
	s_waitcnt lgkmcnt(3)
	v_mfma_f32_32x32x16_bf16 v[96:111], v[80:83], v[136:139], 0
	v_exp_f32_e32 v238, v64
	v_add_f32_e32 v64, 0, v196
	v_add_f32_e32 v64, v197, v64
	v_add_f32_e32 v64, v193, v64
	v_add_f32_e32 v64, v195, v64
	s_waitcnt lgkmcnt(2)
	v_mfma_f32_32x32x16_bf16 v[80:95], v[84:87], v[136:139], 0
	v_add_f32_e32 v64, v191, v64
	v_add_f32_e32 v64, v194, v64
	v_add_f32_e32 v64, v190, v64
	v_add_f32_e32 v64, v192, v64
	v_add_f32_e32 v64, v169, v64
	v_add_f32_e32 v64, v171, v64
	s_waitcnt lgkmcnt(1)
	v_mfma_f32_32x32x16_bf16 v[96:111], v[198:201], v[140:143], v[96:111]
	v_add_f32_e32 v64, v167, v64
	v_add_f32_e32 v64, v170, v64
	v_add_f32_e32 v64, v165, v64
	v_add_f32_e32 v64, v168, v64
	v_add_f32_e32 v64, v164, v64
	v_add_f32_e32 v64, v166, v64
	v_exp_f32_e32 v239, v68
	s_waitcnt lgkmcnt(0)
	v_mfma_f32_32x32x16_bf16 v[80:95], v[202:205], v[140:143], v[80:95]
	ds_read_b128 v[198:201], v180 offset:16384
	ds_read_b128 v[202:205], v180 offset:24576
	v_add_f32_e32 v64, v238, v64
	v_exp_f32_e32 v240, v69
	v_exp_f32_e32 v241, v70
	v_exp_f32_e32 v242, v71
	s_waitcnt lgkmcnt(1)
	v_mfma_f32_32x32x16_bf16 v[96:111], v[198:201], v[132:135], v[96:111]
	ds_read_b128 v[198:201], v181 offset:16384
	ds_read_b128 v[206:209], v181 offset:24576
	ds_read_b128 v[210:213], v182 offset:16384
	ds_read_b128 v[214:217], v182 offset:24576
	ds_read_b128 v[218:221], v183 offset:16384
	ds_read_b128 v[222:225], v183 offset:24576
	v_exp_f32_e32 v243, v76
	v_exp_f32_e32 v244, v77
	v_exp_f32_e32 v245, v78
	v_exp_f32_e32 v79, v79
	s_waitcnt lgkmcnt(6)
	v_mfma_f32_32x32x16_bf16 v[80:95], v[202:205], v[132:135], v[80:95]
	ds_read_b128 v[202:205], v184 offset:16384
	ds_read_b128 v[226:229], v184 offset:24576
	ds_read_b128 v[230:233], v185 offset:16384
	ds_read_b128 v[234:237], v185 offset:24576
	s_waitcnt lgkmcnt(9)
	v_mfma_f32_32x32x16_bf16 v[96:111], v[198:201], v[128:131], v[96:111]
	v_exp_f32_e32 v199, v65
	v_exp_f32_e32 v200, v66
	v_exp_f32_e32 v201, v67
	v_add_f32_e32 v64, v199, v64
	v_add_f32_e32 v64, v200, v64
	v_add_f32_e32 v64, v201, v64
	s_waitcnt lgkmcnt(8)
	v_mfma_f32_32x32x16_bf16 v[80:95], v[206:209], v[128:131], v[80:95]
	v_exp_f32_e32 v206, v72
	v_add_f32_e32 v64, v239, v64
	v_exp_f32_e32 v207, v73
	v_add_f32_e32 v64, v240, v64
	v_exp_f32_e32 v208, v74
	v_add_f32_e32 v64, v241, v64
	v_exp_f32_e32 v209, v75
	s_waitcnt lgkmcnt(7)
	v_mfma_f32_32x32x16_bf16 v[96:111], v[210:213], v[124:127], v[96:111]
	v_add_f32_e32 v64, v242, v64
	v_add_f32_e32 v64, v206, v64
	v_add_f32_e32 v64, v207, v64
	v_add_f32_e32 v64, v208, v64
	v_add_f32_e32 v64, v209, v64
	v_add_f32_e32 v64, v243, v64
	v_add_f32_e32 v64, v244, v64
	s_waitcnt lgkmcnt(6)
	v_mfma_f32_32x32x16_bf16 v[80:95], v[214:217], v[124:127], v[80:95]
	v_add_f32_e32 v64, v245, v64
	v_add_f32_e32 v198, v79, v64
	v_cvt_pk_bf16_f32 v64, v196, v197
	v_cvt_pk_bf16_f32 v65, v193, v195
	v_cvt_pk_bf16_f32 v66, v191, v194
	v_cvt_pk_bf16_f32 v67, v190, v192
	s_waitcnt lgkmcnt(5)
	v_mfma_f32_32x32x16_bf16 v[96:111], v[218:221], v[120:123], v[96:111]
	v_cvt_pk_bf16_f32 v68, v169, v171
	v_cvt_pk_bf16_f32 v69, v167, v170
	v_cvt_pk_bf16_f32 v70, v165, v168
	v_cvt_pk_bf16_f32 v71, v164, v166
	v_cvt_pk_bf16_f32 v72, v238, v199
	v_cvt_pk_bf16_f32 v73, v200, v201
	v_cvt_pk_bf16_f32 v74, v239, v240
	s_waitcnt lgkmcnt(4)
	v_mfma_f32_32x32x16_bf16 v[80:95], v[222:225], v[120:123], v[80:95]
	v_cvt_pk_bf16_f32 v75, v241, v242
	v_cvt_pk_bf16_f32 v76, v206, v207
	v_cvt_pk_bf16_f32 v77, v208, v209
	v_cvt_pk_bf16_f32 v78, v243, v244
	v_cvt_pk_bf16_f32 v79, v245, v79
	s_waitcnt lgkmcnt(3)
	v_mfma_f32_32x32x16_bf16 v[96:111], v[202:205], v[116:119], v[96:111]
	s_add_i32 s33, s40, 0x8000
	s_and_b32 s43, s33, 0xc000
	ds_read_b64_tr_b16 v[190:191], v176
	ds_read_b64_tr_b16 v[192:193], v176 offset:2048
	ds_read_b64_tr_b16 v[194:195], v176 offset:4096
	ds_read_b64_tr_b16 v[196:197], v176 offset:6144
	s_waitcnt lgkmcnt(6)
	v_mfma_f32_32x32x16_bf16 v[80:95], v[226:229], v[116:119], v[80:95]
	ds_read_b64_tr_b16 v[200:201], v176 offset:8192
	ds_read_b64_tr_b16 v[202:203], v176 offset:10240
	ds_read_b64_tr_b16 v[204:205], v176 offset:12288
	ds_read_b64_tr_b16 v[206:207], v176 offset:14336
	s_add_i32 s73, s40, 0x4000
	s_and_b32 s73, s73, 0xc000
	s_add_u32 s98, s38, s22
	s_addc_u32 s99, s39, s23
	s_add_i32 s41, s66, s73
	s_add_u32 s100, s38, s24
	s_addc_u32 s101, s39, s25
	s_mov_b32 m0, s41
	s_add_i32 s73, s67, s73
	global_load_lds_dwordx4 v156, s[98:99]
	s_waitcnt lgkmcnt(9)
	v_mfma_f32_32x32x16_bf16 v[96:111], v[230:233], v[112:115], v[96:111]
	s_add_i32 m0, s41, 0x2000
	s_nop 0
	global_load_lds_dwordx4 v158, s[98:99]
	s_mov_b32 m0, s73
	s_nop 0
	global_load_lds_dwordx4 v162, s[100:101]
	s_waitcnt lgkmcnt(8)
	v_mfma_f32_32x32x16_bf16 v[80:95], v[234:237], v[112:115], v[80:95]
	s_add_i32 m0, s73, 0x2000
	s_nop 0
	global_load_lds_dwordx4 v160, s[100:101]
	s_nop 0
	s_waitcnt lgkmcnt(6)
; #define SBAR() __builtin_amdgcn_sched_barrier(0)
; #define PUBLISH(n) do { asm volatile("s_waitcnt vmcnt(" #n ")" ::: "memory"); asm volatile("s_waitcnt lgkmcnt(0)" ::: "memory"); __builtin_amdgcn_s_barrier(); SBAR(); } while (0)
; template <typename TQ> ...
;     ...
;     pv_d0(o, vb0 + ((j - 1) & 3) * (int)SHM_V, pa0, pa1, pa2, pa3); partialSM<true>(pB0, pB1, m_reg, mnB, alB);
;     PUBLISH(4);
;     SBAR(); qkt(pA0, pA1, (const bf16*)(K_lds + ((j + 1) & 3) * (int)SHM_K), qr, r32, hi);
;     finishSM(pB0, pB1, alB, l_reg, pa0, pa1, pa2, pa3); SBAR();
;     if (j + 3 < NT) { DMA_TILE(j + 3, (j + 3) & 3); } SBAR();
	v_mfma_f32_32x32x16_bf16 v[48:63], v[64:67], v[190:193], v[48:63]
	v_exp_f32_e32 v232, v96
	ds_read_b64_tr_b16 v[190:191], v176 offset:512
	ds_read_b64_tr_b16 v[192:193], v176 offset:2560
	s_waitcnt lgkmcnt(6)
	v_mfma_f32_32x32x16_bf16 v[48:63], v[68:71], v[194:197], v[48:63]
	v_exp_f32_e32 v233, v97
	ds_read_b64_tr_b16 v[194:195], v176 offset:4608
	ds_read_b64_tr_b16 v[196:197], v176 offset:6656
	s_waitcnt lgkmcnt(6)
	v_mfma_f32_32x32x16_bf16 v[48:63], v[72:75], v[200:203], v[48:63]
	v_exp_f32_e32 v234, v98
	ds_read_b64_tr_b16 v[200:201], v176 offset:8704
	ds_read_b64_tr_b16 v[202:203], v176 offset:10752
	ds_read_b64_tr_b16 v[208:209], v176 offset:12800
	ds_read_b64_tr_b16 v[210:211], v176 offset:14848
	s_waitcnt lgkmcnt(8)
	v_mfma_f32_32x32x16_bf16 v[48:63], v[76:79], v[204:207], v[48:63]
	v_exp_f32_e32 v235, v99
	s_waitcnt lgkmcnt(6)
	v_mfma_f32_32x32x16_bf16 v[32:47], v[64:67], v[190:193], v[32:47]
	v_exp_f32_e32 v236, v100
	ds_read_b64_tr_b16 v[190:191], v176 offset:1024
	ds_read_b64_tr_b16 v[192:193], v176 offset:3072
	s_waitcnt lgkmcnt(6)
	v_mfma_f32_32x32x16_bf16 v[32:47], v[68:71], v[194:197], v[32:47]
	v_exp_f32_e32 v237, v101
	ds_read_b64_tr_b16 v[194:195], v176 offset:5120
	ds_read_b64_tr_b16 v[196:197], v176 offset:7168
	s_waitcnt lgkmcnt(6)
	v_mfma_f32_32x32x16_bf16 v[32:47], v[72:75], v[200:203], v[32:47]
	v_exp_f32_e32 v238, v102
	ds_read_b64_tr_b16 v[200:201], v176 offset:9216
	ds_read_b64_tr_b16 v[202:203], v176 offset:11264
	ds_read_b64_tr_b16 v[204:205], v176 offset:13312
	ds_read_b64_tr_b16 v[206:207], v176 offset:15360
	s_waitcnt lgkmcnt(8)
	v_mfma_f32_32x32x16_bf16 v[32:47], v[76:79], v[208:211], v[32:47]
	v_exp_f32_e32 v239, v103
	v_exp_f32_e32 v240, v104
	s_waitcnt lgkmcnt(6)
	v_mfma_f32_32x32x16_bf16 v[16:31], v[64:67], v[190:193], v[16:31]
	v_exp_f32_e32 v241, v105
	ds_read_b64_tr_b16 v[190:191], v176 offset:1536
	ds_read_b64_tr_b16 v[192:193], v176 offset:3584
	s_waitcnt lgkmcnt(6)
	v_mfma_f32_32x32x16_bf16 v[16:31], v[68:71], v[194:197], v[16:31]
	v_exp_f32_e32 v242, v106
	ds_read_b64_tr_b16 v[194:195], v176 offset:5632
	ds_read_b64_tr_b16 v[196:197], v176 offset:7680
	s_waitcnt lgkmcnt(6)
	v_mfma_f32_32x32x16_bf16 v[16:31], v[72:75], v[200:203], v[16:31]
	v_exp_f32_e32 v243, v107
	ds_read_b64_tr_b16 v[200:201], v176 offset:9728
	ds_read_b64_tr_b16 v[202:203], v176 offset:11776
	ds_read_b64_tr_b16 v[208:209], v176 offset:13824
	ds_read_b64_tr_b16 v[210:211], v176 offset:15872
	s_waitcnt lgkmcnt(8)
	v_mfma_f32_32x32x16_bf16 v[16:31], v[76:79], v[204:207], v[16:31]
	v_exp_f32_e32 v244, v108
	s_waitcnt lgkmcnt(6)
	v_mfma_f32_32x32x16_bf16 v[0:15], v[64:67], v[190:193], v[0:15]
	v_exp_f32_e32 v245, v109
	s_waitcnt lgkmcnt(4)
	v_mfma_f32_32x32x16_bf16 v[0:15], v[68:71], v[194:197], v[0:15]
	v_exp_f32_e32 v246, v110
	s_waitcnt lgkmcnt(2)
	v_mfma_f32_32x32x16_bf16 v[0:15], v[72:75], v[200:203], v[0:15]
	v_exp_f32_e32 v247, v111
	s_waitcnt vmcnt(4)
	s_waitcnt lgkmcnt(0)
	s_barrier
	v_mfma_f32_32x32x16_bf16 v[0:15], v[76:79], v[208:211], v[0:15]
	s_and_b32 s40, s40, 0xc000
	s_add_i32 s40, s56, s40
	ds_read_b128 v[64:67], v178 offset:32768
	ds_read_b128 v[68:71], v178 offset:40960
	ds_read_b128 v[190:193], v179 offset:32768
	ds_read_b128 v[194:197], v179 offset:40960
	s_waitcnt lgkmcnt(3)
	v_mfma_f32_32x32x16_bf16 v[96:111], v[64:67], v[136:139], 0
	v_exp_f32_e32 v80, v80
	v_exp_f32_e32 v81, v81
	v_exp_f32_e32 v82, v82
	v_exp_f32_e32 v83, v83
	v_exp_f32_e32 v87, v87
	v_exp_f32_e32 v248, v93
	v_exp_f32_e32 v249, v94
	s_waitcnt lgkmcnt(2)
	v_mfma_f32_32x32x16_bf16 v[64:79], v[68:71], v[136:139], 0
	s_waitcnt lgkmcnt(1)
	v_mfma_f32_32x32x16_bf16 v[96:111], v[190:193], v[140:143], v[96:111]
	s_waitcnt lgkmcnt(0)
	v_mfma_f32_32x32x16_bf16 v[64:79], v[194:197], v[140:143], v[64:79]
	ds_read_b128 v[190:193], v180 offset:32768
	ds_read_b128 v[194:197], v180 offset:40960
	s_waitcnt lgkmcnt(1)
	v_mfma_f32_32x32x16_bf16 v[96:111], v[190:193], v[132:135], v[96:111]
	ds_read_b128 v[190:193], v181 offset:32768
	ds_read_b128 v[200:203], v181 offset:40960
	ds_read_b128 v[204:207], v182 offset:32768
	ds_read_b128 v[208:211], v182 offset:40960
	ds_read_b128 v[212:215], v183 offset:32768
	ds_read_b128 v[216:219], v183 offset:40960
	s_waitcnt lgkmcnt(6)
	v_mfma_f32_32x32x16_bf16 v[64:79], v[194:197], v[132:135], v[64:79]
	ds_read_b128 v[194:197], v184 offset:32768
	ds_read_b128 v[220:223], v184 offset:40960
	ds_read_b128 v[224:227], v185 offset:32768
	ds_read_b128 v[228:231], v185 offset:40960
	s_waitcnt lgkmcnt(9)
	v_mfma_f32_32x32x16_bf16 v[96:111], v[190:193], v[128:131], v[96:111]
	s_cmp_ge_u32 s72, s37
	s_cselect_b64 s[40:41], -1, 0
	s_and_b64 vcc, exec, s[40:41]
	s_cbranch_vccnz .LBB0_1367
	s_add_i32 s73, s66, s43
	s_add_u32 s98, s38, s26
	s_addc_u32 s99, s39, s27
	s_mov_b32 m0, s73
	s_add_i32 s43, s67, s43
	global_load_lds_dwordx4 v156, s[98:99]
	s_add_u32 s100, s38, s28
	s_addc_u32 s101, s39, s29
	s_add_i32 m0, s73, 0x2000
	s_nop 0
	global_load_lds_dwordx4 v158, s[98:99]
	s_mov_b32 m0, s43
	s_nop 0
	global_load_lds_dwordx4 v162, s[100:101]
	s_add_i32 m0, s43, 0x2000
	s_nop 0
	global_load_lds_dwordx4 v160, s[100:101]

; #define SBAR() __builtin_amdgcn_sched_barrier(0)
; template <typename TQ> ...
;     ...
;     SBAR(); qkt(pB0, pB1, (const bf16*)(K_lds + (j & 3) * (int)SHM_K), qr, r32, hi);
;     finishSM(pA0, pA1, alA, l_reg, pa0, pa1, pa2, pa3); SBAR();
;     DMA_TILE(j + 2, (j + 2) & 3); SBAR();
;     pv_d0(o, vb0 + ((j - 1) & 3) * (int)SHM_V, pa0, pa1, pa2, pa3); partialSM<true>(pB0, pB1, m_reg, mnB, alB);
.Lat1365_b:
.Lat1365_b_in:
	s_mov_b32 s40, s33
	s_addk_i32 s33, 0xc000
	s_and_b32 s42, s33, 0xc000
	s_add_i32 s33, s56, s42
	ds_read_b128 v[80:83], v178 offset:49152
	ds_read_b128 v[84:87], v178 offset:57344
	ds_read_b128 v[198:201], v179 offset:49152
	ds_read_b128 v[202:205], v179 offset:57344
	s_waitcnt lgkmcnt(3)
	v_mfma_f32_32x32x16_bf16 v[96:111], v[80:83], v[136:139], 0
	v_exp_f32_e32 v238, v64
	v_add_f32_e32 v64, 0, v196
	v_add_f32_e32 v64, v197, v64
	v_add_f32_e32 v64, v193, v64
	v_add_f32_e32 v64, v195, v64
	s_waitcnt lgkmcnt(2)
	v_mfma_f32_32x32x16_bf16 v[80:95], v[84:87], v[136:139], 0
	v_add_f32_e32 v64, v191, v64
	v_add_f32_e32 v64, v194, v64
	v_add_f32_e32 v64, v190, v64
	v_add_f32_e32 v64, v192, v64
	v_add_f32_e32 v64, v169, v64
	v_add_f32_e32 v64, v171, v64
	s_waitcnt lgkmcnt(1)
	v_mfma_f32_32x32x16_bf16 v[96:111], v[198:201], v[140:143], v[96:111]
	v_add_f32_e32 v64, v167, v64
	v_add_f32_e32 v64, v170, v64
	v_add_f32_e32 v64, v165, v64
	v_add_f32_e32 v64, v168, v64
	v_add_f32_e32 v64, v164, v64
	v_add_f32_e32 v64, v166, v64
	v_exp_f32_e32 v239, v68
	s_waitcnt lgkmcnt(0)
	v_mfma_f32_32x32x16_bf16 v[80:95], v[202:205], v[140:143], v[80:95]
	ds_read_b128 v[198:201], v180 offset:49152
	ds_read_b128 v[202:205], v180 offset:57344
	v_add_f32_e32 v64, v238, v64
	v_exp_f32_e32 v240, v69
	v_exp_f32_e32 v241, v70
	v_exp_f32_e32 v242, v71
	s_waitcnt lgkmcnt(1)
	v_mfma_f32_32x32x16_bf16 v[96:111], v[198:201], v[132:135], v[96:111]
	ds_read_b128 v[198:201], v181 offset:49152
	ds_read_b128 v[206:209], v181 offset:57344
	ds_read_b128 v[210:213], v182 offset:49152
	ds_read_b128 v[214:217], v182 offset:57344
	ds_read_b128 v[218:221], v183 offset:49152
	ds_read_b128 v[222:225], v183 offset:57344
	v_exp_f32_e32 v243, v76
	v_exp_f32_e32 v244, v77
	v_exp_f32_e32 v245, v78
	v_exp_f32_e32 v79, v79
	s_waitcnt lgkmcnt(6)
	v_mfma_f32_32x32x16_bf16 v[80:95], v[202:205], v[132:135], v[80:95]
	ds_read_b128 v[202:205], v184 offset:49152
	ds_read_b128 v[226:229], v184 offset:57344
	ds_read_b128 v[230:233], v185 offset:49152
	ds_read_b128 v[234:237], v185 offset:57344
	s_waitcnt lgkmcnt(9)
	v_mfma_f32_32x32x16_bf16 v[96:111], v[198:201], v[128:131], v[96:111]
	v_exp_f32_e32 v199, v65
	v_exp_f32_e32 v200, v66
	v_exp_f32_e32 v201, v67
	v_add_f32_e32 v64, v199, v64
	v_add_f32_e32 v64, v200, v64
	v_add_f32_e32 v64, v201, v64
	s_waitcnt lgkmcnt(8)
	v_mfma_f32_32x32x16_bf16 v[80:95], v[206:209], v[128:131], v[80:95]
	v_exp_f32_e32 v206, v72
	v_add_f32_e32 v64, v239, v64
	v_exp_f32_e32 v207, v73
	v_add_f32_e32 v64, v240, v64
	v_exp_f32_e32 v208, v74
	v_add_f32_e32 v64, v241, v64
	v_exp_f32_e32 v209, v75
	s_waitcnt lgkmcnt(7)
	v_mfma_f32_32x32x16_bf16 v[96:111], v[210:213], v[124:127], v[96:111]
	v_add_f32_e32 v64, v242, v64
	v_add_f32_e32 v64, v206, v64
	v_add_f32_e32 v64, v207, v64
	v_add_f32_e32 v64, v208, v64
	v_add_f32_e32 v64, v209, v64
	v_add_f32_e32 v64, v243, v64
	v_add_f32_e32 v64, v244, v64
	s_waitcnt lgkmcnt(6)
	v_mfma_f32_32x32x16_bf16 v[80:95], v[214:217], v[124:127], v[80:95]
	v_add_f32_e32 v64, v245, v64
	v_add_f32_e32 v198, v79, v64
	v_cvt_pk_bf16_f32 v64, v196, v197
	v_cvt_pk_bf16_f32 v65, v193, v195
	v_cvt_pk_bf16_f32 v66, v191, v194
	v_cvt_pk_bf16_f32 v67, v190, v192
	s_waitcnt lgkmcnt(5)
	v_mfma_f32_32x32x16_bf16 v[96:111], v[218:221], v[120:123], v[96:111]
	v_cvt_pk_bf16_f32 v68, v169, v171
	v_cvt_pk_bf16_f32 v69, v167, v170
	v_cvt_pk_bf16_f32 v70, v165, v168
	v_cvt_pk_bf16_f32 v71, v164, v166
	v_cvt_pk_bf16_f32 v72, v238, v199
	v_cvt_pk_bf16_f32 v73, v200, v201
	v_cvt_pk_bf16_f32 v74, v239, v240
	s_waitcnt lgkmcnt(4)
	v_mfma_f32_32x32x16_bf16 v[80:95], v[222:225], v[120:123], v[80:95]
	v_cvt_pk_bf16_f32 v75, v241, v242
	v_cvt_pk_bf16_f32 v76, v206, v207
	v_cvt_pk_bf16_f32 v77, v208, v209
	v_cvt_pk_bf16_f32 v78, v243, v244
	v_cvt_pk_bf16_f32 v79, v245, v79
	s_waitcnt lgkmcnt(3)
	v_mfma_f32_32x32x16_bf16 v[96:111], v[202:205], v[116:119], v[96:111]
	s_add_i32 s33, s40, 0x8000
	s_and_b32 s43, s33, 0xc000
	ds_read_b64_tr_b16 v[190:191], v176 offset:32768
	ds_read_b64_tr_b16 v[192:193], v176 offset:34816
	ds_read_b64_tr_b16 v[194:195], v176 offset:36864
	ds_read_b64_tr_b16 v[196:197], v176 offset:38912
	s_waitcnt lgkmcnt(6)
	v_mfma_f32_32x32x16_bf16 v[80:95], v[226:229], v[116:119], v[80:95]
	ds_read_b64_tr_b16 v[200:201], v176 offset:40960
	ds_read_b64_tr_b16 v[202:203], v176 offset:43008
	ds_read_b64_tr_b16 v[204:205], v176 offset:45056
	ds_read_b64_tr_b16 v[206:207], v176 offset:47104
	s_add_i32 s73, s40, 0x4000
	s_and_b32 s73, s73, 0xc000
	s_add_u32 s98, s38, s22
	s_addc_u32 s99, s39, s23
	s_add_i32 s41, s66, s73
	s_add_u32 s100, s38, s24
	s_addc_u32 s101, s39, s25
	s_mov_b32 m0, s41
	s_add_i32 s73, s67, s73
	global_load_lds_dwordx4 v156, s[98:99]
	s_waitcnt lgkmcnt(9)
	v_mfma_f32_32x32x16_bf16 v[96:111], v[230:233], v[112:115], v[96:111]
	s_add_i32 m0, s41, 0x2000
	s_nop 0
	global_load_lds_dwordx4 v158, s[98:99]
	s_mov_b32 m0, s73
	s_nop 0
	global_load_lds_dwordx4 v162, s[100:101]
	s_waitcnt lgkmcnt(8)
; #define SBAR() __builtin_amdgcn_sched_barrier(0)
; #define PUBLISH(n) do { asm volatile("s_waitcnt vmcnt(" #n ")" ::: "memory"); asm volatile("s_waitcnt lgkmcnt(0)" ::: "memory"); __builtin_amdgcn_s_barrier(); SBAR(); } while (0)
; template <typename TQ> ...
;     ...
;     pv_d0(o, vb0 + ((j - 1) & 3) * (int)SHM_V, pa0, pa1, pa2, pa3); partialSM<true>(pB0, pB1, m_reg, mnB, alB);
;     PUBLISH(4);
;     SBAR(); qkt(pA0, pA1, (const bf16*)(K_lds + ((j + 1) & 3) * (int)SHM_K), qr, r32, hi);
;     finishSM(pB0, pB1, alB, l_reg, pa0, pa1, pa2, pa3); SBAR();
;     if (j + 3 < NT) { DMA_TILE(j + 3, (j + 3) & 3); } SBAR();
	v_mfma_f32_32x32x16_bf16 v[80:95], v[234:237], v[112:115], v[80:95]
	s_add_i32 m0, s73, 0x2000
	s_nop 0
	global_load_lds_dwordx4 v160, s[100:101]
	s_nop 0
	s_waitcnt lgkmcnt(6)
	v_mfma_f32_32x32x16_bf16 v[48:63], v[64:67], v[190:193], v[48:63]
	v_exp_f32_e32 v232, v96
	ds_read_b64_tr_b16 v[190:191], v176 offset:33280
	ds_read_b64_tr_b16 v[192:193], v176 offset:35328
	s_waitcnt lgkmcnt(6)
	v_mfma_f32_32x32x16_bf16 v[48:63], v[68:71], v[194:197], v[48:63]
	v_exp_f32_e32 v233, v97
	ds_read_b64_tr_b16 v[194:195], v176 offset:37376
	ds_read_b64_tr_b16 v[196:197], v176 offset:39424
	s_waitcnt lgkmcnt(6)
	v_mfma_f32_32x32x16_bf16 v[48:63], v[72:75], v[200:203], v[48:63]
	v_exp_f32_e32 v234, v98
	ds_read_b64_tr_b16 v[200:201], v176 offset:41472
	ds_read_b64_tr_b16 v[202:203], v176 offset:43520
	ds_read_b64_tr_b16 v[208:209], v176 offset:45568
	ds_read_b64_tr_b16 v[210:211], v176 offset:47616
	s_waitcnt lgkmcnt(8)
	v_mfma_f32_32x32x16_bf16 v[48:63], v[76:79], v[204:207], v[48:63]
	v_exp_f32_e32 v235, v99
	s_waitcnt lgkmcnt(6)
	v_mfma_f32_32x32x16_bf16 v[32:47], v[64:67], v[190:193], v[32:47]
	v_exp_f32_e32 v236, v100
	ds_read_b64_tr_b16 v[190:191], v176 offset:33792
	ds_read_b64_tr_b16 v[192:193], v176 offset:35840
	s_waitcnt lgkmcnt(6)
	v_mfma_f32_32x32x16_bf16 v[32:47], v[68:71], v[194:197], v[32:47]
	v_exp_f32_e32 v237, v101
	ds_read_b64_tr_b16 v[194:195], v176 offset:37888
	ds_read_b64_tr_b16 v[196:197], v176 offset:39936
	s_waitcnt lgkmcnt(6)
	v_mfma_f32_32x32x16_bf16 v[32:47], v[72:75], v[200:203], v[32:47]
	v_exp_f32_e32 v238, v102
	ds_read_b64_tr_b16 v[200:201], v176 offset:41984
	ds_read_b64_tr_b16 v[202:203], v176 offset:44032
	ds_read_b64_tr_b16 v[204:205], v176 offset:46080
	ds_read_b64_tr_b16 v[206:207], v176 offset:48128
	s_waitcnt lgkmcnt(8)
	v_mfma_f32_32x32x16_bf16 v[32:47], v[76:79], v[208:211], v[32:47]
	v_exp_f32_e32 v239, v103
	v_exp_f32_e32 v240, v104
	s_waitcnt lgkmcnt(6)
	v_mfma_f32_32x32x16_bf16 v[16:31], v[64:67], v[190:193], v[16:31]
	v_exp_f32_e32 v241, v105
	ds_read_b64_tr_b16 v[190:191], v176 offset:34304
	ds_read_b64_tr_b16 v[192:193], v176 offset:36352
	s_waitcnt lgkmcnt(6)
	v_mfma_f32_32x32x16_bf16 v[16:31], v[68:71], v[194:197], v[16:31]
	v_exp_f32_e32 v242, v106
	ds_read_b64_tr_b16 v[194:195], v176 offset:38400
	ds_read_b64_tr_b16 v[196:197], v176 offset:40448
	s_waitcnt lgkmcnt(6)
	v_mfma_f32_32x32x16_bf16 v[16:31], v[72:75], v[200:203], v[16:31]
	v_exp_f32_e32 v243, v107
	ds_read_b64_tr_b16 v[200:201], v176 offset:42496
	ds_read_b64_tr_b16 v[202:203], v176 offset:44544
	ds_read_b64_tr_b16 v[208:209], v176 offset:46592
	ds_read_b64_tr_b16 v[210:211], v176 offset:48640
	s_waitcnt lgkmcnt(8)
	v_mfma_f32_32x32x16_bf16 v[16:31], v[76:79], v[204:207], v[16:31]
	v_exp_f32_e32 v244, v108
	s_waitcnt lgkmcnt(6)
	v_mfma_f32_32x32x16_bf16 v[0:15], v[64:67], v[190:193], v[0:15]
	v_exp_f32_e32 v245, v109
	s_waitcnt lgkmcnt(4)
	v_mfma_f32_32x32x16_bf16 v[0:15], v[68:71], v[194:197], v[0:15]
	v_exp_f32_e32 v246, v110
	s_waitcnt lgkmcnt(2)
	v_mfma_f32_32x32x16_bf16 v[0:15], v[72:75], v[200:203], v[0:15]
	v_exp_f32_e32 v247, v111
	s_waitcnt vmcnt(4)
	s_waitcnt lgkmcnt(0)
	s_barrier
	v_mfma_f32_32x32x16_bf16 v[0:15], v[76:79], v[208:211], v[0:15]
	s_and_b32 s40, s40, 0xc000
	s_add_i32 s40, s56, s40
	ds_read_b128 v[64:67], v178
	ds_read_b128 v[68:71], v178 offset:8192
	ds_read_b128 v[190:193], v179
	ds_read_b128 v[194:197], v179 offset:8192
	s_waitcnt lgkmcnt(3)
	v_mfma_f32_32x32x16_bf16 v[96:111], v[64:67], v[136:139], 0
	v_exp_f32_e32 v80, v80
	v_exp_f32_e32 v81, v81
	v_exp_f32_e32 v82, v82
	v_exp_f32_e32 v83, v83
	v_exp_f32_e32 v87, v87
	v_exp_f32_e32 v248, v93
	v_exp_f32_e32 v249, v94
	s_waitcnt lgkmcnt(2)
	v_mfma_f32_32x32x16_bf16 v[64:79], v[68:71], v[136:139], 0
	s_waitcnt lgkmcnt(1)
	v_mfma_f32_32x32x16_bf16 v[96:111], v[190:193], v[140:143], v[96:111]
	s_waitcnt lgkmcnt(0)
	v_mfma_f32_32x32x16_bf16 v[64:79], v[194:197], v[140:143], v[64:79]
	ds_read_b128 v[190:193], v180
	ds_read_b128 v[194:197], v180 offset:8192
	s_waitcnt lgkmcnt(1)
	v_mfma_f32_32x32x16_bf16 v[96:111], v[190:193], v[132:135], v[96:111]
	ds_read_b128 v[190:193], v181
	ds_read_b128 v[200:203], v181 offset:8192
	ds_read_b128 v[204:207], v182
	ds_read_b128 v[208:211], v182 offset:8192
	ds_read_b128 v[212:215], v183
	ds_read_b128 v[216:219], v183 offset:8192
	s_waitcnt lgkmcnt(6)
	v_mfma_f32_32x32x16_bf16 v[64:79], v[194:197], v[132:135], v[64:79]
	ds_read_b128 v[194:197], v184
	ds_read_b128 v[220:223], v184 offset:8192
	ds_read_b128 v[224:227], v185
	ds_read_b128 v[228:231], v185 offset:8192
	s_waitcnt lgkmcnt(9)
	v_mfma_f32_32x32x16_bf16 v[96:111], v[190:193], v[128:131], v[96:111]
	s_cmp_ge_u32 s72, s37
	s_cselect_b64 s[40:41], -1, 0
	s_and_b64 vcc, exec, s[40:41]
	s_cbranch_vccnz .Lat1367_b

; #define SBAR() __builtin_amdgcn_sched_barrier(0)
; template <typename TQ> ...
;     ...
;     if (j + 3 < NT) { DMA_TILE(j + 3, (j + 3) & 3); } SBAR();
	s_add_i32 s73, s66, s43
	s_add_u32 s98, s38, s26
	s_addc_u32 s99, s39, s27
	s_mov_b32 m0, s73
	s_add_i32 s43, s67, s43
	global_load_lds_dwordx4 v156, s[98:99]
	s_add_u32 s100, s38, s28
	s_addc_u32 s101, s39, s29
	s_add_i32 m0, s73, 0x2000
	s_nop 0
	global_load_lds_dwordx4 v158, s[98:99]
	s_mov_b32 m0, s43
	s_nop 0
	global_load_lds_dwordx4 v162, s[100:101]
	s_add_i32 m0, s43, 0x2000
	s_nop 0
	global_load_lds_dwordx4 v160, s[100:101]

; #define SBAR() __builtin_amdgcn_sched_barrier(0)
; template <typename TQ> ...
;     ...
;   SBAR(); qkt(pB0, pB1, (const bf16*)(K_lds + ((NT - 1) & 3) * (int)SHM_K), qr, r32, hi);
;   finishSM(pA0, pA1, alA, l_reg, pa0, pa1, pa2, pa3); SBAR();
;   pv_d0(o, vb0 + ((NT - 2) & 3) * (int)SHM_V, pa0, pa1, pa2, pa3); partialSM<true>(pB0, pB1, m_reg, mnB, alB);
.LBB0_1371:
	v_add_u32_e32 v178, 0xffff0000, v178
	v_add_u32_e32 v179, 0xffff0000, v179
	v_add_u32_e32 v180, 0xffff0000, v180
	v_add_u32_e32 v181, 0xffff0000, v181
	v_add_u32_e32 v182, 0xffff0000, v182
	v_add_u32_e32 v183, 0xffff0000, v183
	v_add_u32_e32 v184, 0xffff0000, v184
	v_add_u32_e32 v185, 0xffff0000, v185
	s_and_b32 s33, s65, 0x3fffffc0
	s_lshl_b32 s33, s33, 2
	s_add_i32 s33, s33, 0
	s_add_i32 s33, s33, 0x20000
	v_add_u32_e32 v84, s59, v178
	ds_read_b128 v[80:83], v84
	ds_read_b128 v[84:87], v84 offset:8192
	v_add_u32_e32 v156, s59, v179
	v_add_u32_e32 v160, s59, v181
	v_exp_f32_e32 v218, v64
	s_waitcnt lgkmcnt(0)
	v_mfma_f32_32x32x16_bf16 v[96:111], v[80:83], v[136:139], 0
	v_add_f32_e32 v64, 0, v196
	v_add_f32_e32 v64, v197, v64
	v_add_f32_e32 v64, v193, v64
	v_add_u32_e32 v198, s59, v182
	v_add_f32_e32 v64, v195, v64
	v_add_f32_e32 v64, v191, v64
	v_add_f32_e32 v64, v194, v64
	v_mfma_f32_32x32x16_bf16 v[80:95], v[84:87], v[136:139], 0
	ds_read_b128 v[136:139], v156
	ds_read_b128 v[156:159], v156 offset:8192
	v_add_f32_e32 v64, v190, v64
	v_add_f32_e32 v64, v192, v64
	v_add_f32_e32 v64, v169, v64
	v_add_f32_e32 v64, v171, v64
	v_add_f32_e32 v64, v167, v64
	v_add_u32_e32 v206, s59, v183
	s_waitcnt lgkmcnt(0)
	v_mfma_f32_32x32x16_bf16 v[96:111], v[136:139], v[140:143], v[96:111]
	v_add_f32_e32 v64, v170, v64
	v_add_f32_e32 v64, v165, v64
	v_exp_f32_e32 v219, v65
	v_add_f32_e32 v64, v168, v64
	v_add_f32_e32 v64, v164, v64
	v_add_f32_e32 v64, v166, v64
	v_add_f32_e32 v64, v218, v64
	v_mfma_f32_32x32x16_bf16 v[80:95], v[156:159], v[140:143], v[80:95]
	v_add_u32_e32 v140, s59, v180
	ds_read_b128 v[136:139], v140
	ds_read_b128 v[140:143], v140 offset:8192
	ds_read_b128 v[156:159], v160
	ds_read_b128 v[160:163], v160 offset:8192
	v_add_f32_e32 v64, v219, v64
	v_exp_f32_e32 v220, v70
	v_add_u32_e32 v210, s59, v184
	v_exp_f32_e32 v221, v71
	s_waitcnt lgkmcnt(0)
	v_mfma_f32_32x32x16_bf16 v[96:111], v[136:139], v[132:135], v[96:111]
	ds_read_b128 v[136:139], v198
	ds_read_b128 v[198:201], v198 offset:8192
	ds_read_b128 v[202:205], v206
	ds_read_b128 v[206:209], v206 offset:8192
	v_exp_f32_e32 v222, v72
	v_add_u32_e32 v214, s59, v185
	v_exp_f32_e32 v79, v79
	v_mfma_f32_32x32x16_bf16 v[80:95], v[140:143], v[132:135], v[80:95]
	ds_read_b128 v[132:135], v210
	ds_read_b128 v[140:143], v210 offset:8192
	ds_read_b128 v[210:213], v214
	ds_read_b128 v[214:217], v214 offset:8192
	v_mfma_f32_32x32x16_bf16 v[96:111], v[156:159], v[128:131], v[96:111]
	v_exp_f32_e32 v156, v66
	v_exp_f32_e32 v157, v67
	v_exp_f32_e32 v158, v68
	v_exp_f32_e32 v159, v69
	v_add_f32_e32 v64, v156, v64
	v_add_f32_e32 v64, v157, v64
	v_add_f32_e32 v64, v158, v64
	v_mfma_f32_32x32x16_bf16 v[80:95], v[160:163], v[128:131], v[80:95]
	v_exp_f32_e32 v128, v73
	v_add_f32_e32 v64, v159, v64
	v_exp_f32_e32 v129, v74
	v_add_f32_e32 v64, v220, v64
	v_exp_f32_e32 v130, v75
	v_add_f32_e32 v64, v221, v64
	v_exp_f32_e32 v131, v76
	s_waitcnt lgkmcnt(0)
	v_mfma_f32_32x32x16_bf16 v[96:111], v[136:139], v[124:127], v[96:111]
	v_add_f32_e32 v64, v222, v64
	v_exp_f32_e32 v160, v77
	v_add_f32_e32 v64, v128, v64
	v_exp_f32_e32 v161, v78
	v_add_f32_e32 v64, v129, v64
	v_add_f32_e32 v64, v130, v64
	v_add_f32_e32 v64, v131, v64
	v_mfma_f32_32x32x16_bf16 v[80:95], v[198:201], v[124:127], v[80:95]
	v_add_f32_e32 v64, v160, v64
	v_add_f32_e32 v64, v161, v64
	v_add_f32_e32 v64, v79, v64
	v_mfma_f32_32x32x16_bf16 v[96:111], v[202:205], v[120:123], v[96:111]
	v_mfma_f32_32x32x16_bf16 v[80:95], v[206:209], v[120:123], v[80:95]
	v_mfma_f32_32x32x16_bf16 v[96:111], v[132:135], v[116:119], v[96:111]
	v_add_f32_e32 v132, v146, v64
	v_cvt_pk_bf16_f32 v64, v196, v197
	v_cvt_pk_bf16_f32 v65, v193, v195
	v_cvt_pk_bf16_f32 v66, v191, v194
	v_cvt_pk_bf16_f32 v67, v190, v192
	v_cvt_pk_bf16_f32 v68, v169, v171
	v_cvt_pk_bf16_f32 v69, v167, v170
	v_mfma_f32_32x32x16_bf16 v[80:95], v[140:143], v[116:119], v[80:95]
	v_cvt_pk_bf16_f32 v70, v165, v168
	v_cvt_pk_bf16_f32 v71, v164, v166
	v_cvt_pk_bf16_f32 v72, v218, v219
	v_cvt_pk_bf16_f32 v73, v156, v157
	v_cvt_pk_bf16_f32 v74, v158, v159
	v_cvt_pk_bf16_f32 v75, v220, v221
	v_cvt_pk_bf16_f32 v76, v222, v128
	v_mfma_f32_32x32x16_bf16 v[96:111], v[210:213], v[112:115], v[96:111]
	v_cvt_pk_bf16_f32 v77, v129, v130
	v_cvt_pk_bf16_f32 v78, v131, v160
	v_cvt_pk_bf16_f32 v79, v161, v79
	v_mfma_f32_32x32x16_bf16 v[80:95], v[214:217], v[112:115], v[80:95]
	ds_read_b64_tr_b16 v[112:113], v186 offset:0
	ds_read_b64_tr_b16 v[114:115], v186 offset:0x800
	ds_read_b64_tr_b16 v[116:117], v186 offset:0x1000
	ds_read_b64_tr_b16 v[118:119], v186 offset:0x1800
	ds_read_b64_tr_b16 v[120:121], v186 offset:0x2000
	ds_read_b64_tr_b16 v[122:123], v186 offset:0x2800
	ds_read_b64_tr_b16 v[124:125], v186 offset:0x3000
	ds_read_b64_tr_b16 v[126:127], v186 offset:0x3800
	s_waitcnt lgkmcnt(0)
	s_nop 0
	v_mfma_f32_32x32x16_bf16 v[48:63], v[64:67], v[112:115], v[48:63]
	ds_read_b64_tr_b16 v[112:113], v186 offset:0x200
	ds_read_b64_tr_b16 v[114:115], v186 offset:0xa00
	v_mfma_f32_32x32x16_bf16 v[48:63], v[68:71], v[116:119], v[48:63]
	ds_read_b64_tr_b16 v[116:117], v186 offset:0x1200
	ds_read_b64_tr_b16 v[118:119], v186 offset:0x1a00
	v_mfma_f32_32x32x16_bf16 v[48:63], v[72:75], v[120:123], v[48:63]
	ds_read_b64_tr_b16 v[120:121], v186 offset:0x2200
	ds_read_b64_tr_b16 v[122:123], v186 offset:0x2a00
	ds_read_b64_tr_b16 v[128:129], v186 offset:0x3200
	ds_read_b64_tr_b16 v[130:131], v186 offset:0x3a00
	s_waitcnt lgkmcnt(0)
; #define SBAR() __builtin_amdgcn_sched_barrier(0)
; template <typename TQ> ...
;     ...
;   pv_d0(o, vb0 + ((NT - 2) & 3) * (int)SHM_V, pa0, pa1, pa2, pa3); partialSM<true>(pB0, pB1, m_reg, mnB, alB);
;   finishSM(pB0, pB1, alB, l_reg, pa0, pa1, pa2, pa3); SBAR();
;   pv_d0(o, vb0 + ((NT - 1) & 3) * (int)SHM_V, pa0, pa1, pa2, pa3);
;   { auto rr = __builtin_amdgcn_permlane32_swap(__float_as_uint(l_reg), __float_as_uint(l_reg), false, false); l_reg = __uint_as_float(rr[0]) + __uint_as_float(rr[1]); }
;   if (hi == 0) li_l[r32] = l_reg; asm volatile("s_waitcnt lgkmcnt(0)" ::: "memory");
	v_mfma_f32_32x32x16_bf16 v[48:63], v[76:79], v[124:127], v[48:63]
	v_mfma_f32_32x32x16_bf16 v[32:47], v[64:67], v[112:115], v[32:47]
	ds_read_b64_tr_b16 v[112:113], v186 offset:0x400
	ds_read_b64_tr_b16 v[114:115], v186 offset:0xc00
	v_mfma_f32_32x32x16_bf16 v[32:47], v[68:71], v[116:119], v[32:47]
	ds_read_b64_tr_b16 v[116:117], v186 offset:0x1400
	ds_read_b64_tr_b16 v[118:119], v186 offset:0x1c00
	v_mfma_f32_32x32x16_bf16 v[32:47], v[72:75], v[120:123], v[32:47]
	ds_read_b64_tr_b16 v[120:121], v186 offset:0x2400
	ds_read_b64_tr_b16 v[122:123], v186 offset:0x2c00
	ds_read_b64_tr_b16 v[124:125], v186 offset:0x3400
	ds_read_b64_tr_b16 v[126:127], v186 offset:0x3c00
	s_waitcnt lgkmcnt(0)
	v_mfma_f32_32x32x16_bf16 v[32:47], v[76:79], v[128:131], v[32:47]
	v_mfma_f32_32x32x16_bf16 v[16:31], v[64:67], v[112:115], v[16:31]
	ds_read_b64_tr_b16 v[112:113], v186 offset:0x600
	ds_read_b64_tr_b16 v[114:115], v186 offset:0xe00
	v_mfma_f32_32x32x16_bf16 v[16:31], v[68:71], v[116:119], v[16:31]
	ds_read_b64_tr_b16 v[116:117], v186 offset:0x1600
	ds_read_b64_tr_b16 v[118:119], v186 offset:0x1e00
	v_mfma_f32_32x32x16_bf16 v[16:31], v[72:75], v[120:123], v[16:31]
	ds_read_b64_tr_b16 v[120:121], v186 offset:0x2600
	ds_read_b64_tr_b16 v[122:123], v186 offset:0x2e00
	ds_read_b64_tr_b16 v[128:129], v186 offset:0x3600
	ds_read_b64_tr_b16 v[130:131], v186 offset:0x3e00
	s_waitcnt lgkmcnt(0)
	v_mfma_f32_32x32x16_bf16 v[16:31], v[76:79], v[124:127], v[16:31]
	v_exp_f32_e32 v96, v96
	v_exp_f32_e32 v97, v97
	v_exp_f32_e32 v98, v98
	v_exp_f32_e32 v99, v99
	v_mfma_f32_32x32x16_bf16 v[0:15], v[64:67], v[112:115], v[0:15]
	v_exp_f32_e32 v100, v100
	v_add_f32_e32 v64, 0, v96
	v_exp_f32_e32 v101, v101
	v_add_f32_e32 v64, v97, v64
	v_exp_f32_e32 v65, v102
	v_add_f32_e32 v64, v98, v64
	v_exp_f32_e32 v102, v103
	v_add_f32_e32 v64, v99, v64
	v_exp_f32_e32 v103, v104
	v_add_f32_e32 v64, v100, v64
	v_exp_f32_e32 v104, v105
	v_add_f32_e32 v64, v101, v64
	v_exp_f32_e32 v105, v106
	v_add_f32_e32 v64, v65, v64
	v_exp_f32_e32 v106, v107
	v_mfma_f32_32x32x16_bf16 v[0:15], v[68:71], v[116:119], v[0:15]
	v_add_f32_e32 v64, v102, v64
	v_exp_f32_e32 v107, v108
	v_add_f32_e32 v64, v103, v64
	v_exp_f32_e32 v108, v109
	v_add_f32_e32 v64, v104, v64
	v_exp_f32_e32 v109, v110
	v_add_f32_e32 v64, v105, v64
	v_exp_f32_e32 v110, v111
	v_add_f32_e32 v64, v106, v64
	v_exp_f32_e32 v80, v80
	v_add_f32_e32 v64, v107, v64
	v_exp_f32_e32 v81, v81
	v_add_f32_e32 v64, v108, v64
	v_exp_f32_e32 v82, v82
	v_add_f32_e32 v64, v109, v64
	v_exp_f32_e32 v83, v83
	v_mfma_f32_32x32x16_bf16 v[0:15], v[72:75], v[120:123], v[0:15]
	v_add_f32_e32 v64, v110, v64
	v_exp_f32_e32 v84, v84
	v_add_f32_e32 v64, v80, v64
	v_exp_f32_e32 v85, v85
	v_add_f32_e32 v64, v81, v64
	v_exp_f32_e32 v86, v86
	v_add_f32_e32 v64, v82, v64
	v_exp_f32_e32 v87, v87
	v_add_f32_e32 v64, v83, v64
	v_exp_f32_e32 v88, v88
	v_add_f32_e32 v64, v84, v64
	v_exp_f32_e32 v89, v89
	v_add_f32_e32 v64, v85, v64
	v_exp_f32_e32 v90, v90
	v_add_f32_e32 v64, v86, v64
	v_mfma_f32_32x32x16_bf16 v[0:15], v[76:79], v[128:131], v[0:15]
	v_exp_f32_e32 v79, v91
	v_add_f32_e32 v64, v87, v64
	v_exp_f32_e32 v91, v92
	v_add_f32_e32 v64, v88, v64
	v_exp_f32_e32 v92, v93
	v_add_f32_e32 v64, v89, v64
	v_exp_f32_e32 v93, v94
	v_add_f32_e32 v64, v90, v64
	v_exp_f32_e32 v94, v95
	v_add_f32_e32 v64, v79, v64
	v_add_f32_e32 v64, v91, v64
	v_add_f32_e32 v64, v92, v64
	v_add_f32_e32 v64, v93, v64
	v_add_f32_e32 v64, v94, v64
	v_cvt_pk_bf16_f32 v66, v96, v97
	v_cvt_pk_bf16_f32 v67, v98, v99
	v_cvt_pk_bf16_f32 v68, v100, v101
	v_cvt_pk_bf16_f32 v69, v65, v102
	v_cvt_pk_bf16_f32 v70, v103, v104
	s_nop 0
	v_add_f32_e32 v64, v132, v64
	v_cvt_pk_bf16_f32 v71, v105, v106
	v_cvt_pk_bf16_f32 v72, v107, v108
	v_cvt_pk_bf16_f32 v73, v109, v110
	v_cvt_pk_bf16_f32 v74, v80, v81
	v_cvt_pk_bf16_f32 v75, v82, v83
	v_cvt_pk_bf16_f32 v76, v84, v85
	v_cvt_pk_bf16_f32 v77, v86, v87
	v_cvt_pk_bf16_f32 v78, v88, v89
	v_cvt_pk_bf16_f32 v79, v90, v79
	v_cvt_pk_bf16_f32 v80, v91, v92
	v_cvt_pk_bf16_f32 v81, v93, v94
	ds_read_b64_tr_b16 v[82:83], v187 offset:0
	ds_read_b64_tr_b16 v[84:85], v187 offset:0x800
	ds_read_b64_tr_b16 v[86:87], v187 offset:0x1000
	ds_read_b64_tr_b16 v[88:89], v187 offset:0x1800
	ds_read_b64_tr_b16 v[90:91], v187 offset:0x2000
	ds_read_b64_tr_b16 v[92:93], v187 offset:0x2800
	ds_read_b64_tr_b16 v[94:95], v187 offset:0x3000
	ds_read_b64_tr_b16 v[96:97], v187 offset:0x3800
	s_waitcnt lgkmcnt(0)
	s_nop 0
	v_mfma_f32_32x32x16_bf16 v[48:63], v[66:69], v[82:85], v[48:63]
	ds_read_b64_tr_b16 v[82:83], v187 offset:0x200
	ds_read_b64_tr_b16 v[84:85], v187 offset:0xa00
	v_mfma_f32_32x32x16_bf16 v[48:63], v[70:73], v[86:89], v[48:63]
	ds_read_b64_tr_b16 v[86:87], v187 offset:0x1200
	ds_read_b64_tr_b16 v[88:89], v187 offset:0x1a00
	v_mfma_f32_32x32x16_bf16 v[48:63], v[74:77], v[90:93], v[48:63]
	ds_read_b64_tr_b16 v[90:91], v187 offset:0x2200
	ds_read_b64_tr_b16 v[92:93], v187 offset:0x2a00
	ds_read_b64_tr_b16 v[98:99], v187 offset:0x3200
	ds_read_b64_tr_b16 v[100:101], v187 offset:0x3a00
	s_waitcnt lgkmcnt(0)
	v_mfma_f32_32x32x16_bf16 v[48:63], v[78:81], v[94:97], v[48:63]
	v_mfma_f32_32x32x16_bf16 v[32:47], v[66:69], v[82:85], v[32:47]
	ds_read_b64_tr_b16 v[82:83], v187 offset:0x400
	ds_read_b64_tr_b16 v[84:85], v187 offset:0xc00
	v_mfma_f32_32x32x16_bf16 v[32:47], v[70:73], v[86:89], v[32:47]
	ds_read_b64_tr_b16 v[86:87], v187 offset:0x1400
	ds_read_b64_tr_b16 v[88:89], v187 offset:0x1c00
	v_mfma_f32_32x32x16_bf16 v[32:47], v[74:77], v[90:93], v[32:47]
	ds_read_b64_tr_b16 v[90:91], v187 offset:0x2400
	ds_read_b64_tr_b16 v[92:93], v187 offset:0x2c00
	ds_read_b64_tr_b16 v[94:95], v187 offset:0x3400
	ds_read_b64_tr_b16 v[96:97], v187 offset:0x3c00
	s_waitcnt lgkmcnt(0)
	v_mfma_f32_32x32x16_bf16 v[32:47], v[78:81], v[98:101], v[32:47]
	v_mfma_f32_32x32x16_bf16 v[16:31], v[66:69], v[82:85], v[16:31]
	ds_read_b64_tr_b16 v[82:83], v187 offset:0x600
	ds_read_b64_tr_b16 v[84:85], v187 offset:0xe00
	v_mfma_f32_32x32x16_bf16 v[16:31], v[70:73], v[86:89], v[16:31]
	ds_read_b64_tr_b16 v[86:87], v187 offset:0x1600
	ds_read_b64_tr_b16 v[88:89], v187 offset:0x1e00
	v_mfma_f32_32x32x16_bf16 v[16:31], v[74:77], v[90:93], v[16:31]
	ds_read_b64_tr_b16 v[90:91], v187 offset:0x2600
	ds_read_b64_tr_b16 v[92:93], v187 offset:0x2e00
	ds_read_b64_tr_b16 v[98:99], v187 offset:0x3600
	ds_read_b64_tr_b16 v[100:101], v187 offset:0x3e00
	s_waitcnt lgkmcnt(0)
	v_mfma_f32_32x32x16_bf16 v[16:31], v[78:81], v[94:97], v[16:31]
	v_mfma_f32_32x32x16_bf16 v[0:15], v[66:69], v[82:85], v[0:15]
	v_mov_b32_e32 v65, v64
	s_nop 1
	v_permlane32_swap_b32_e32 v64, v65
	v_mfma_f32_32x32x16_bf16 v[0:15], v[70:73], v[86:89], v[0:15]
	v_mfma_f32_32x32x16_bf16 v[0:15], v[74:77], v[90:93], v[0:15]
	v_mfma_f32_32x32x16_bf16 v[0:15], v[78:81], v[98:101], v[0:15]
	s_and_saveexec_b64 s[38:39], s[2:3]
	s_cbranch_execz .LBB0_1358
	v_lshl_add_u32 v66, v144, 2, s33
	v_add_f32_e32 v64, v64, v65
	ds_write_b32 v66, v64
	s_branch .LBB0_1358
